# cache policy: nt (streaming) hint on the 41 P0 write-once bf16 stores (converted weights, x->XB0 rows, p) so dirty lines drain continuously instead of at the grid-sync wbl2; on top of v025
# speedup vs baseline: 1.0070x; 1.0070x over previous
; #define LAS __attribute__((address_space(3)))
; __device__ __forceinline__ unsigned pk2(float lo, float hi) { return f2bf(lo) | (f2bf(hi) << 16); }
; #define LDS_WAIT() asm volatile("s_waitcnt lgkmcnt(0)" ::: "memory")
; __device__ __forceinline__ void cv_process(const CvDesc& d, int lane, const f32x4 (&v)[16], const f32x4& g0, const f32x4& g1, LAS float* scr) {
;     const int nblk = d.N / 64, kb = d.r / nblk, nb = d.r % nblk, k0 = 64 * kb, n0 = 64 * nb;
;     const int lk = lane >> 4, n4 = (lane & 15) * 4, c = lane & 7;
; #pragma unroll
;     for (int j = 0; j < 16; ++j) { const int k = 4 * j + lk; *(LAS f32x4*)(scr + k * 64 + (n4 ^ (8 * ((k >> 3) & 7)))) = v[j]; }
;     LDS_WAIT(); asm volatile("" ::: "memory");
; #pragma unroll
;     for (int j = 0; j < 8; ++j) { const int n = (lane >> 3) + 8 * j; const LAS float* s = scr + (8 * c) * 64 + (n ^ (8 * c));
;         u32x4 o; o.x = pk2(s[0 * 64] * g0[0], s[1 * 64] * g0[1]); o.y = pk2(s[2 * 64] * g0[2], s[3 * 64] * g0[3]); o.z = pk2(s[4 * 64] * g1[0], s[5 * 64] * g1[1]); o.w = pk2(s[6 * 64] * g1[2], s[7 * 64] * g1[3]);
;         const int ng = n0 + n, drow = d.mode ? (((ng >> 7) << 8) + (ng & 127) + d.off) : (d.off + ng);
;         *(u32x4*)(d.dst + (size_t)drow * d.K + k0 + 8 * c) = o; }
.Lcv_ladB_done:
	v_ashrrev_i32_e32 v164, 31, v205
	s_waitcnt lgkmcnt(0)
	v_mul_f32_e32 v5, 0x4f7ffffe, v5
	v_cvt_u32_f32_e32 v5, v5
	v_mul_lo_u32 v166, v166, v5
	v_mul_hi_u32 v166, v5, v166
	v_add_u32_e32 v5, v5, v166
	v_mul_hi_u32 v5, v165, v5
	v_mul_lo_u32 v166, v5, v4
	v_sub_u32_e32 v165, v165, v166
	v_add_u32_e32 v167, 1, v5
	v_cmp_ge_u32_e64 s[4:5], v165, v4
	v_sub_u32_e32 v166, v165, v4
	s_nop 0
	v_cndmask_b32_e64 v5, v5, v167, s[4:5]
	v_cndmask_b32_e64 v165, v165, v166, s[4:5]
	v_add_u32_e32 v166, 1, v5
	v_cmp_ge_u32_e64 s[4:5], v165, v4
	s_nop 1
	v_cndmask_b32_e64 v5, v5, v166, s[4:5]
	v_xor_b32_e32 v5, v5, v164
	v_sub_u32_e32 v5, v5, v164
	ds_read2st64_b32 v[164:165], v185 offset1:1
	ds_read2st64_b32 v[168:169], v185 offset0:2 offset1:3
	v_mul_lo_u32 v4, v5, v4
	ds_read2st64_b32 v[208:209], v185 offset0:4 offset1:5
	ds_read2st64_b32 v[210:211], v185 offset0:6 offset1:7
	v_sub_u32_e32 v4, v205, v4
	v_lshlrev_b32_e32 v206, 6, v4
	v_lshlrev_b32_e32 v4, 7, v4
	v_lshlrev_b32_e32 v170, 6, v5
	v_and_b32_e32 v207, 0xffffff00, v4
	v_mov_b32_e32 v4, v142
	v_mov_b32_e32 v5, v144
	s_waitcnt lgkmcnt(3)
	v_mov_b32_e32 v166, v164
	s_waitcnt lgkmcnt(2)
	v_mov_b32_e32 v167, v168
	v_pk_mul_f32 v[212:213], v[4:5], v[166:167]
	v_mov_b32_e32 v166, v143
	v_mov_b32_e32 v167, v145
	v_mov_b32_e32 v168, v165
	v_pk_mul_f32 v[214:215], v[166:167], v[168:169]
	v_mov_b32_e32 v164, v146
	v_mov_b32_e32 v165, v148
	s_waitcnt lgkmcnt(1)
	v_mov_b32_e32 v168, v208
	s_waitcnt lgkmcnt(0)
	v_mov_b32_e32 v169, v210
	v_pk_mul_f32 v[216:217], v[164:165], v[168:169]
	v_mov_b32_e32 v168, v147
	v_mov_b32_e32 v169, v149
	v_mov_b32_e32 v210, v209
	v_pk_mul_f32 v[208:209], v[168:169], v[210:211]
	v_bfe_u32 v218, v215, 16, 1
	v_bfe_u32 v210, v209, 16, 1
	v_bfe_u32 v211, v208, 16, 1
	v_bfe_u32 v219, v214, 16, 1
	v_add3_u32 v215, v215, v218, s55
	v_add3_u32 v209, v209, v210, s55
	v_bfe_u32 v210, v212, 16, 1
	v_bfe_u32 v218, v216, 16, 1
	v_add3_u32 v214, v214, v219, s55
	v_add3_u32 v208, v208, v211, s55
	v_bfe_u32 v211, v213, 16, 1
	v_bfe_u32 v219, v217, 16, 1
	v_add3_u32 v216, v216, v218, s55
	v_add3_u32 v210, v212, v210, s55
	v_add3_u32 v217, v217, v219, s55
	v_add3_u32 v211, v213, v211, s55
	v_lshrrev_b32_e32 v212, 16, v210
	v_lshrrev_b32_e32 v210, 16, v216
	v_lshrrev_b32_e32 v213, 16, v211
	v_lshrrev_b32_e32 v211, 16, v217
	v_and_or_b32 v210, v208, s56, v210
	v_and_or_b32 v208, v214, s56, v212
	v_or_b32_e32 v212, v206, v184
	v_and_or_b32 v211, v209, s56, v211
	v_and_or_b32 v209, v215, s56, v213
	v_and_or_b32 v213, v212, s57, v207
	v_cmp_eq_u32_e64 s[4:5], 0, v203
	v_ashrrev_i32_e32 v171, 31, v170
	v_lshlrev_b64 v[170:171], 1, v[170:171]
	v_cndmask_b32_e64 v212, v213, v212, s[4:5]
	v_add_u32_e32 v212, v212, v204
	v_ashrrev_i32_e32 v215, 31, v212
	v_mad_u64_u32 v[212:213], s[0:1], v212, v202, 0
	v_mov_b32_e32 v214, v213
	v_mad_u64_u32 v[214:215], s[0:1], v215, v202, v[214:215]
	v_mov_b32_e32 v213, v214
	v_lshl_add_u64 v[212:213], v[212:213], 1, v[160:161]
	v_lshl_add_u64 v[212:213], v[212:213], 0, v[170:171]
	v_lshl_add_u64 v[212:213], v[212:213], 0, v[162:163]
	ds_read2st64_b32 v[214:215], v187 offset1:1
	ds_read2st64_b32 v[216:217], v187 offset0:2 offset1:3
	global_store_dwordx4 v[212:213], v[208:211], off nt
	ds_read2st64_b32 v[208:209], v187 offset0:4 offset1:5
	ds_read2st64_b32 v[210:211], v187 offset0:6 offset1:7
	s_waitcnt lgkmcnt(3)
	v_mov_b32_e32 v212, v214
	s_waitcnt lgkmcnt(2)
	v_mov_b32_e32 v213, v216
	v_mov_b32_e32 v216, v215
	v_pk_mul_f32 v[214:215], v[166:167], v[216:217]
	s_waitcnt lgkmcnt(0)
	v_mov_b32_e32 v217, v210
	v_mov_b32_e32 v210, v209
	v_mov_b32_e32 v216, v208
	v_pk_mul_f32 v[208:209], v[168:169], v[210:211]
	v_pk_mul_f32 v[212:213], v[4:5], v[212:213]
	v_pk_mul_f32 v[216:217], v[164:165], v[216:217]
	v_bfe_u32 v210, v209, 16, 1
	v_bfe_u32 v218, v215, 16, 1
	v_bfe_u32 v211, v208, 16, 1
	v_bfe_u32 v219, v214, 16, 1
	v_add3_u32 v215, v215, v218, s55
	v_add3_u32 v209, v209, v210, s55
	v_bfe_u32 v210, v212, 16, 1
	v_bfe_u32 v218, v216, 16, 1
	v_add3_u32 v214, v214, v219, s55
	v_add3_u32 v208, v208, v211, s55
	v_bfe_u32 v211, v213, 16, 1
	v_bfe_u32 v219, v217, 16, 1
	v_add3_u32 v216, v216, v218, s55
	v_add3_u32 v210, v212, v210, s55
	v_add3_u32 v217, v217, v219, s55
	v_add3_u32 v211, v213, v211, s55
	v_lshrrev_b32_e32 v212, 16, v210
	v_lshrrev_b32_e32 v210, 16, v216
	v_lshrrev_b32_e32 v213, 16, v211
	v_lshrrev_b32_e32 v211, 16, v217
	v_and_or_b32 v210, v208, s56, v210
	v_and_or_b32 v208, v214, s56, v212
	v_or_b32_e32 v212, v206, v186
	v_and_or_b32 v211, v209, s56, v211
	v_and_or_b32 v209, v215, s56, v213
	v_and_or_b32 v213, v212, s62, v207
	v_cndmask_b32_e64 v212, v213, v212, s[4:5]
	v_add_u32_e32 v212, v212, v204
	v_ashrrev_i32_e32 v215, 31, v212
	v_mad_u64_u32 v[212:213], s[0:1], v212, v202, 0
	v_mov_b32_e32 v214, v213
	v_mad_u64_u32 v[214:215], s[0:1], v215, v202, v[214:215]
	v_mov_b32_e32 v213, v214
	v_lshl_add_u64 v[212:213], v[212:213], 1, v[160:161]
	v_lshl_add_u64 v[212:213], v[212:213], 0, v[170:171]
	v_lshl_add_u64 v[212:213], v[212:213], 0, v[162:163]
	ds_read2st64_b32 v[214:215], v189 offset1:1
	ds_read2st64_b32 v[216:217], v189 offset0:2 offset1:3
	global_store_dwordx4 v[212:213], v[208:211], off nt
	ds_read2st64_b32 v[208:209], v189 offset0:4 offset1:5
	ds_read2st64_b32 v[210:211], v189 offset0:6 offset1:7
	s_waitcnt lgkmcnt(3)
	v_mov_b32_e32 v212, v214
	s_waitcnt lgkmcnt(2)
	v_mov_b32_e32 v213, v216
	v_mov_b32_e32 v216, v215
	v_pk_mul_f32 v[214:215], v[166:167], v[216:217]
	s_waitcnt lgkmcnt(0)
; #define LAS __attribute__((address_space(3)))
; __device__ __forceinline__ unsigned pk2(float lo, float hi) { return f2bf(lo) | (f2bf(hi) << 16); }
; __device__ __forceinline__ void cv_process(const CvDesc& d, int lane, const f32x4 (&v)[16], const f32x4& g0, const f32x4& g1, LAS float* scr) {
;     ...
;     for (int j = 0; j < 8; ++j) { const int n = (lane >> 3) + 8 * j; const LAS float* s = scr + (8 * c) * 64 + (n ^ (8 * c));
;         u32x4 o; o.x = pk2(s[0 * 64] * g0[0], s[1 * 64] * g0[1]); o.y = pk2(s[2 * 64] * g0[2], s[3 * 64] * g0[3]); o.z = pk2(s[4 * 64] * g1[0], s[5 * 64] * g1[1]); o.w = pk2(s[6 * 64] * g1[2], s[7 * 64] * g1[3]);
;         const int ng = n0 + n, drow = d.mode ? (((ng >> 7) << 8) + (ng & 127) + d.off) : (d.off + ng);
;         *(u32x4*)(d.dst + (size_t)drow * d.K + k0 + 8 * c) = o; }
	v_mov_b32_e32 v217, v210
	v_mov_b32_e32 v210, v209
	v_mov_b32_e32 v216, v208
	v_pk_mul_f32 v[208:209], v[168:169], v[210:211]
	v_pk_mul_f32 v[212:213], v[4:5], v[212:213]
	v_pk_mul_f32 v[216:217], v[164:165], v[216:217]
	v_bfe_u32 v210, v209, 16, 1
	v_bfe_u32 v218, v215, 16, 1
	v_bfe_u32 v211, v208, 16, 1
	v_bfe_u32 v219, v214, 16, 1
	v_add3_u32 v215, v215, v218, s55
	v_add3_u32 v209, v209, v210, s55
	v_bfe_u32 v210, v212, 16, 1
	v_bfe_u32 v218, v216, 16, 1
	v_add3_u32 v214, v214, v219, s55
	v_add3_u32 v208, v208, v211, s55
	v_bfe_u32 v211, v213, 16, 1
	v_bfe_u32 v219, v217, 16, 1
	v_add3_u32 v216, v216, v218, s55
	v_add3_u32 v210, v212, v210, s55
	v_add3_u32 v217, v217, v219, s55
	v_add3_u32 v211, v213, v211, s55
	v_lshrrev_b32_e32 v212, 16, v210
	v_lshrrev_b32_e32 v210, 16, v216
	v_lshrrev_b32_e32 v213, 16, v211
	v_lshrrev_b32_e32 v211, 16, v217
	v_and_or_b32 v210, v208, s56, v210
	v_and_or_b32 v208, v214, s56, v212
	v_or_b32_e32 v212, v206, v188
	v_and_or_b32 v211, v209, s56, v211
	v_and_or_b32 v209, v215, s56, v213
	v_and_or_b32 v213, v212, s63, v207
	v_cndmask_b32_e64 v212, v213, v212, s[4:5]
	v_add_u32_e32 v212, v212, v204
	v_ashrrev_i32_e32 v215, 31, v212
	v_mad_u64_u32 v[212:213], s[0:1], v212, v202, 0
	v_mov_b32_e32 v214, v213
	v_mad_u64_u32 v[214:215], s[0:1], v215, v202, v[214:215]
	v_mov_b32_e32 v213, v214
	v_lshl_add_u64 v[212:213], v[212:213], 1, v[160:161]
	v_lshl_add_u64 v[212:213], v[212:213], 0, v[170:171]
	v_lshl_add_u64 v[212:213], v[212:213], 0, v[162:163]
	ds_read2st64_b32 v[214:215], v191 offset1:1
	ds_read2st64_b32 v[216:217], v191 offset0:2 offset1:3
	global_store_dwordx4 v[212:213], v[208:211], off nt
	ds_read2st64_b32 v[208:209], v191 offset0:4 offset1:5
	ds_read2st64_b32 v[210:211], v191 offset0:6 offset1:7
	s_waitcnt lgkmcnt(3)
	v_mov_b32_e32 v212, v214
	s_waitcnt lgkmcnt(2)
	v_mov_b32_e32 v213, v216
	v_mov_b32_e32 v216, v215
	v_pk_mul_f32 v[214:215], v[166:167], v[216:217]
	s_waitcnt lgkmcnt(0)
	v_mov_b32_e32 v217, v210
	v_mov_b32_e32 v210, v209
	v_mov_b32_e32 v216, v208
	v_pk_mul_f32 v[208:209], v[168:169], v[210:211]
	v_pk_mul_f32 v[212:213], v[4:5], v[212:213]
	v_pk_mul_f32 v[216:217], v[164:165], v[216:217]
	v_bfe_u32 v210, v209, 16, 1
	v_bfe_u32 v218, v215, 16, 1
	v_bfe_u32 v211, v208, 16, 1
	v_bfe_u32 v219, v214, 16, 1
	v_add3_u32 v215, v215, v218, s55
	v_add3_u32 v209, v209, v210, s55
	v_bfe_u32 v210, v212, 16, 1
	v_bfe_u32 v218, v216, 16, 1
	v_add3_u32 v214, v214, v219, s55
	v_add3_u32 v208, v208, v211, s55
	v_bfe_u32 v211, v213, 16, 1
	v_bfe_u32 v219, v217, 16, 1
	v_add3_u32 v216, v216, v218, s55
	v_add3_u32 v210, v212, v210, s55
	v_add3_u32 v217, v217, v219, s55
	v_add3_u32 v211, v213, v211, s55
	v_lshrrev_b32_e32 v212, 16, v210
	v_lshrrev_b32_e32 v210, 16, v216
	v_lshrrev_b32_e32 v213, 16, v211
	v_lshrrev_b32_e32 v211, 16, v217
	v_and_or_b32 v210, v208, s56, v210
	v_and_or_b32 v208, v214, s56, v212
	v_or_b32_e32 v212, v206, v190
	v_and_or_b32 v211, v209, s56, v211
	v_and_or_b32 v209, v215, s56, v213
	v_and_or_b32 v213, v212, s64, v207
	v_cndmask_b32_e64 v212, v213, v212, s[4:5]
	v_add_u32_e32 v212, v212, v204
	v_ashrrev_i32_e32 v215, 31, v212
	v_mad_u64_u32 v[212:213], s[0:1], v212, v202, 0
	v_mov_b32_e32 v214, v213
	v_mad_u64_u32 v[214:215], s[0:1], v215, v202, v[214:215]
	v_mov_b32_e32 v213, v214
	v_lshl_add_u64 v[212:213], v[212:213], 1, v[160:161]
	v_lshl_add_u64 v[212:213], v[212:213], 0, v[170:171]
	v_lshl_add_u64 v[212:213], v[212:213], 0, v[162:163]
	ds_read2st64_b32 v[214:215], v193 offset1:1
	ds_read2st64_b32 v[216:217], v193 offset0:2 offset1:3
	global_store_dwordx4 v[212:213], v[208:211], off nt
	ds_read2st64_b32 v[208:209], v193 offset0:4 offset1:5
	ds_read2st64_b32 v[210:211], v193 offset0:6 offset1:7
	s_waitcnt lgkmcnt(3)
	v_mov_b32_e32 v212, v214
	s_waitcnt lgkmcnt(2)
	v_mov_b32_e32 v213, v216
	v_mov_b32_e32 v216, v215
	v_pk_mul_f32 v[214:215], v[166:167], v[216:217]
	s_waitcnt lgkmcnt(0)
	v_mov_b32_e32 v217, v210
	v_mov_b32_e32 v210, v209
	v_mov_b32_e32 v216, v208
	v_pk_mul_f32 v[208:209], v[168:169], v[210:211]
	v_pk_mul_f32 v[212:213], v[4:5], v[212:213]
	v_pk_mul_f32 v[216:217], v[164:165], v[216:217]
	v_bfe_u32 v210, v209, 16, 1
	v_bfe_u32 v218, v215, 16, 1
	v_bfe_u32 v211, v208, 16, 1
	v_bfe_u32 v219, v214, 16, 1
	v_add3_u32 v215, v215, v218, s55
	v_add3_u32 v209, v209, v210, s55
	v_bfe_u32 v210, v212, 16, 1
	v_bfe_u32 v218, v216, 16, 1
	v_add3_u32 v214, v214, v219, s55
	v_add3_u32 v208, v208, v211, s55
	v_bfe_u32 v211, v213, 16, 1
	v_bfe_u32 v219, v217, 16, 1
	v_add3_u32 v216, v216, v218, s55
	v_add3_u32 v210, v212, v210, s55
	v_add3_u32 v217, v217, v219, s55
	v_add3_u32 v211, v213, v211, s55
	v_lshrrev_b32_e32 v212, 16, v210
	v_lshrrev_b32_e32 v210, 16, v216
	v_lshrrev_b32_e32 v213, 16, v211
	v_lshrrev_b32_e32 v211, 16, v217
	v_and_or_b32 v210, v208, s56, v210
	v_and_or_b32 v208, v214, s56, v212
	v_or_b32_e32 v212, v206, v192
	v_and_or_b32 v211, v209, s56, v211
	v_and_or_b32 v209, v215, s56, v213
	v_and_or_b32 v213, v212, s65, v207
	v_cndmask_b32_e64 v212, v213, v212, s[4:5]
	v_add_u32_e32 v212, v212, v204
	v_ashrrev_i32_e32 v215, 31, v212
	v_mad_u64_u32 v[212:213], s[0:1], v212, v202, 0
	v_mov_b32_e32 v214, v213
	v_mad_u64_u32 v[214:215], s[0:1], v215, v202, v[214:215]
	v_mov_b32_e32 v213, v214
	v_lshl_add_u64 v[212:213], v[212:213], 1, v[160:161]
	v_lshl_add_u64 v[212:213], v[212:213], 0, v[170:171]
	v_lshl_add_u64 v[212:213], v[212:213], 0, v[162:163]
	ds_read2st64_b32 v[214:215], v195 offset1:1
	ds_read2st64_b32 v[216:217], v195 offset0:2 offset1:3
	global_store_dwordx4 v[212:213], v[208:211], off nt
	ds_read2st64_b32 v[208:209], v195 offset0:4 offset1:5
	ds_read2st64_b32 v[210:211], v195 offset0:6 offset1:7
	s_waitcnt lgkmcnt(3)
; #define LAS __attribute__((address_space(3)))
; __device__ __forceinline__ unsigned pk2(float lo, float hi) { return f2bf(lo) | (f2bf(hi) << 16); }
; __device__ __forceinline__ void cv_process(const CvDesc& d, int lane, const f32x4 (&v)[16], const f32x4& g0, const f32x4& g1, LAS float* scr) {
;     ...
;     for (int j = 0; j < 8; ++j) { const int n = (lane >> 3) + 8 * j; const LAS float* s = scr + (8 * c) * 64 + (n ^ (8 * c));
;         u32x4 o; o.x = pk2(s[0 * 64] * g0[0], s[1 * 64] * g0[1]); o.y = pk2(s[2 * 64] * g0[2], s[3 * 64] * g0[3]); o.z = pk2(s[4 * 64] * g1[0], s[5 * 64] * g1[1]); o.w = pk2(s[6 * 64] * g1[2], s[7 * 64] * g1[3]);
;         const int ng = n0 + n, drow = d.mode ? (((ng >> 7) << 8) + (ng & 127) + d.off) : (d.off + ng);
;         *(u32x4*)(d.dst + (size_t)drow * d.K + k0 + 8 * c) = o; }
	v_mov_b32_e32 v212, v214
	s_waitcnt lgkmcnt(2)
	v_mov_b32_e32 v213, v216
	v_mov_b32_e32 v216, v215
	v_pk_mul_f32 v[214:215], v[166:167], v[216:217]
	s_waitcnt lgkmcnt(0)
	v_mov_b32_e32 v217, v210
	v_mov_b32_e32 v210, v209
	v_mov_b32_e32 v216, v208
	v_pk_mul_f32 v[208:209], v[168:169], v[210:211]
	v_pk_mul_f32 v[212:213], v[4:5], v[212:213]
	v_pk_mul_f32 v[216:217], v[164:165], v[216:217]
	v_bfe_u32 v210, v209, 16, 1
	v_bfe_u32 v218, v215, 16, 1
	v_bfe_u32 v211, v208, 16, 1
	v_bfe_u32 v219, v214, 16, 1
	v_add3_u32 v215, v215, v218, s55
	v_add3_u32 v209, v209, v210, s55
	v_bfe_u32 v210, v212, 16, 1
	v_bfe_u32 v218, v216, 16, 1
	v_add3_u32 v214, v214, v219, s55
	v_add3_u32 v208, v208, v211, s55
	v_bfe_u32 v211, v213, 16, 1
	v_bfe_u32 v219, v217, 16, 1
	v_add3_u32 v216, v216, v218, s55
	v_add3_u32 v210, v212, v210, s55
	v_add3_u32 v217, v217, v219, s55
	v_add3_u32 v211, v213, v211, s55
	v_lshrrev_b32_e32 v212, 16, v210
	v_lshrrev_b32_e32 v210, 16, v216
	v_lshrrev_b32_e32 v213, 16, v211
	v_lshrrev_b32_e32 v211, 16, v217
	v_and_or_b32 v210, v208, s56, v210
	v_and_or_b32 v208, v214, s56, v212
	v_or_b32_e32 v212, v206, v194
	v_and_or_b32 v211, v209, s56, v211
	v_and_or_b32 v209, v215, s56, v213
	v_and_or_b32 v213, v212, s66, v207
	v_cndmask_b32_e64 v212, v213, v212, s[4:5]
	v_add_u32_e32 v212, v212, v204
	v_ashrrev_i32_e32 v215, 31, v212
	v_mad_u64_u32 v[212:213], s[0:1], v212, v202, 0
	v_mov_b32_e32 v214, v213
	v_mad_u64_u32 v[214:215], s[0:1], v215, v202, v[214:215]
	v_mov_b32_e32 v213, v214
	v_lshl_add_u64 v[212:213], v[212:213], 1, v[160:161]
	v_lshl_add_u64 v[212:213], v[212:213], 0, v[170:171]
	v_lshl_add_u64 v[212:213], v[212:213], 0, v[162:163]
	ds_read2st64_b32 v[214:215], v197 offset1:1
	ds_read2st64_b32 v[216:217], v197 offset0:2 offset1:3
	global_store_dwordx4 v[212:213], v[208:211], off nt
	ds_read2st64_b32 v[208:209], v197 offset0:4 offset1:5
	ds_read2st64_b32 v[210:211], v197 offset0:6 offset1:7
	s_waitcnt lgkmcnt(3)
	v_mov_b32_e32 v212, v214
	s_waitcnt lgkmcnt(2)
	v_mov_b32_e32 v213, v216
	v_mov_b32_e32 v216, v215
	v_pk_mul_f32 v[214:215], v[166:167], v[216:217]
	s_waitcnt lgkmcnt(0)
	v_mov_b32_e32 v217, v210
	v_mov_b32_e32 v210, v209
	v_mov_b32_e32 v216, v208
	v_pk_mul_f32 v[208:209], v[168:169], v[210:211]
	v_pk_mul_f32 v[212:213], v[4:5], v[212:213]
	v_pk_mul_f32 v[216:217], v[164:165], v[216:217]
	v_bfe_u32 v210, v209, 16, 1
	v_bfe_u32 v218, v215, 16, 1
	v_bfe_u32 v211, v208, 16, 1
	v_bfe_u32 v219, v214, 16, 1
	v_add3_u32 v215, v215, v218, s55
	v_add3_u32 v209, v209, v210, s55
	v_bfe_u32 v210, v212, 16, 1
	v_bfe_u32 v218, v216, 16, 1
	v_add3_u32 v214, v214, v219, s55
	v_add3_u32 v208, v208, v211, s55
	v_bfe_u32 v211, v213, 16, 1
	v_bfe_u32 v219, v217, 16, 1
	v_add3_u32 v216, v216, v218, s55
	v_add3_u32 v210, v212, v210, s55
	v_add3_u32 v217, v217, v219, s55
	v_add3_u32 v211, v213, v211, s55
	v_lshrrev_b32_e32 v212, 16, v210
	v_lshrrev_b32_e32 v210, 16, v216
	v_lshrrev_b32_e32 v213, 16, v211
	v_lshrrev_b32_e32 v211, 16, v217
	v_and_or_b32 v210, v208, s56, v210
	v_and_or_b32 v208, v214, s56, v212
	v_or_b32_e32 v212, v206, v196
	v_and_or_b32 v211, v209, s56, v211
	v_and_or_b32 v209, v215, s56, v213
	v_and_or_b32 v213, v212, s67, v207
	v_cndmask_b32_e64 v212, v213, v212, s[4:5]
	v_add_u32_e32 v212, v212, v204
	v_ashrrev_i32_e32 v215, 31, v212
	v_mad_u64_u32 v[212:213], s[0:1], v212, v202, 0
	v_mov_b32_e32 v214, v213
	v_mad_u64_u32 v[214:215], s[0:1], v215, v202, v[214:215]
	v_mov_b32_e32 v213, v214
	v_lshl_add_u64 v[212:213], v[212:213], 1, v[160:161]
	v_lshl_add_u64 v[212:213], v[212:213], 0, v[170:171]
	v_lshl_add_u64 v[212:213], v[212:213], 0, v[162:163]
	global_store_dwordx4 v[212:213], v[208:211], off nt
	ds_read2st64_b32 v[208:209], v199 offset1:1
	ds_read2st64_b32 v[210:211], v199 offset0:2 offset1:3
	ds_read2st64_b32 v[212:213], v199 offset0:4 offset1:5
	ds_read2st64_b32 v[214:215], v199 offset0:6 offset1:7
	v_or_b32_e32 v206, v206, v198
	v_and_or_b32 v207, v206, s54, v207
	v_cndmask_b32_e64 v206, v207, v206, s[4:5]
	v_add_u32_e32 v216, v206, v204
	s_waitcnt lgkmcnt(3)
	v_mov_b32_e32 v206, v209
	s_waitcnt lgkmcnt(2)
	v_mov_b32_e32 v207, v211
	v_pk_mul_f32 v[166:167], v[166:167], v[206:207]
	s_waitcnt lgkmcnt(1)
	v_mov_b32_e32 v206, v213
	s_waitcnt lgkmcnt(0)
	v_mov_b32_e32 v207, v215
	v_mov_b32_e32 v209, v210
	v_pk_mul_f32 v[168:169], v[168:169], v[206:207]
	v_mov_b32_e32 v213, v214
	v_pk_mul_f32 v[4:5], v[4:5], v[208:209]
	v_pk_mul_f32 v[164:165], v[164:165], v[212:213]
	v_bfe_u32 v206, v169, 16, 1
	v_bfe_u32 v207, v168, 16, 1
	v_bfe_u32 v208, v167, 16, 1
	v_bfe_u32 v209, v166, 16, 1
	v_add3_u32 v209, v166, v209, s55
	v_add3_u32 v208, v167, v208, s55
	v_add3_u32 v166, v168, v207, s55
	v_add3_u32 v167, v169, v206, s55
	v_bfe_u32 v168, v4, 16, 1
	v_bfe_u32 v169, v5, 16, 1
	v_bfe_u32 v206, v164, 16, 1
	v_bfe_u32 v207, v165, 16, 1
	v_add3_u32 v165, v165, v207, s55
	v_add3_u32 v164, v164, v206, s55
	v_add3_u32 v5, v5, v169, s55
	v_add3_u32 v4, v4, v168, s55
	v_lshrrev_b32_e32 v4, 16, v4
	v_lshrrev_b32_e32 v5, 16, v5
	v_lshrrev_b32_e32 v164, 16, v164
	v_lshrrev_b32_e32 v165, 16, v165
	v_and_or_b32 v167, v167, s56, v165
	v_and_or_b32 v166, v166, s56, v164
	v_and_or_b32 v165, v208, s56, v5
	v_and_or_b32 v164, v209, s56, v4
	v_mad_u64_u32 v[4:5], s[0:1], v216, v202, 0
	v_ashrrev_i32_e32 v169, 31, v216
	v_mov_b32_e32 v168, v5
	v_mad_u64_u32 v[168:169], s[0:1], v169, v202, v[168:169]
	v_mov_b32_e32 v5, v168
	v_lshl_add_u64 v[4:5], v[4:5], 1, v[160:161]
	v_lshl_add_u64 v[4:5], v[4:5], 0, v[170:171]
	v_lshl_add_u64 v[4:5], v[4:5], 0, v[162:163]
	global_store_dwordx4 v[4:5], v[164:167], off nt
	s_waitcnt lgkmcnt(0)
	s_and_b64 s[0:1], vcc, exec

; #define LAS __attribute__((address_space(3)))
; __device__ __forceinline__ unsigned pk2(float lo, float hi) { return f2bf(lo) | (f2bf(hi) << 16); }
; #define LDS_WAIT() asm volatile("s_waitcnt lgkmcnt(0)" ::: "memory")
; __device__ __forceinline__ void cv_process(const CvDesc& d, int lane, const f32x4 (&v)[16], const f32x4& g0, const f32x4& g1, LAS float* scr) {
;     const int nblk = d.N / 64, kb = d.r / nblk, nb = d.r % nblk, k0 = 64 * kb, n0 = 64 * nb;
;     const int lk = lane >> 4, n4 = (lane & 15) * 4, c = lane & 7;
; #pragma unroll
;     for (int j = 0; j < 16; ++j) { const int k = 4 * j + lk; *(LAS f32x4*)(scr + k * 64 + (n4 ^ (8 * ((k >> 3) & 7)))) = v[j]; }
;     LDS_WAIT(); asm volatile("" ::: "memory");
; #pragma unroll
;     for (int j = 0; j < 8; ++j) { const int n = (lane >> 3) + 8 * j; const LAS float* s = scr + (8 * c) * 64 + (n ^ (8 * c));
;         u32x4 o; o.x = pk2(s[0 * 64] * g0[0], s[1 * 64] * g0[1]); o.y = pk2(s[2 * 64] * g0[2], s[3 * 64] * g0[3]); o.z = pk2(s[4 * 64] * g1[0], s[5 * 64] * g1[1]); o.w = pk2(s[6 * 64] * g1[2], s[7 * 64] * g1[3]);
;         const int ng = n0 + n, drow = d.mode ? (((ng >> 7) << 8) + (ng & 127) + d.off) : (d.off + ng);
;         *(u32x4*)(d.dst + (size_t)drow * d.K + k0 + 8 * c) = o; }
.Lcv_ladA_done:
	s_waitcnt lgkmcnt(0)
	v_ashrrev_i32_e32 v162, 31, v174
	v_mul_f32_e32 v5, 0x4f7ffffe, v5
	v_cvt_u32_f32_e32 v5, v5
	v_mul_lo_u32 v164, v164, v5
	v_mul_hi_u32 v164, v5, v164
	v_add_u32_e32 v5, v5, v164
	v_mul_hi_u32 v5, v163, v5
	v_mul_lo_u32 v164, v5, v4
	v_sub_u32_e32 v163, v163, v164
	v_add_u32_e32 v165, 1, v5
	v_cmp_ge_u32_e64 s[4:5], v163, v4
	v_sub_u32_e32 v164, v163, v4
	s_nop 0
	v_cndmask_b32_e64 v5, v5, v165, s[4:5]
	v_cndmask_b32_e64 v163, v163, v164, s[4:5]
	v_add_u32_e32 v164, 1, v5
	v_cmp_ge_u32_e64 s[4:5], v163, v4
	s_nop 1
	v_cndmask_b32_e64 v5, v5, v164, s[4:5]
	v_xor_b32_e32 v5, v5, v162
	ds_read2st64_b32 v[164:165], v185 offset1:1
	ds_read2st64_b32 v[168:169], v185 offset0:2 offset1:3
	v_sub_u32_e32 v5, v5, v162
	v_mul_lo_u32 v4, v5, v4
	ds_read2st64_b32 v[170:171], v185 offset0:4 offset1:5
	ds_read2st64_b32 v[210:211], v185 offset0:6 offset1:7
	v_sub_u32_e32 v4, v174, v4
	v_lshlrev_b32_e32 v207, 6, v4
	v_lshlrev_b32_e32 v4, 7, v4
	v_lshlrev_b32_e32 v162, 6, v5
	v_and_b32_e32 v208, 0xffffff00, v4
	v_mov_b32_e32 v4, v70
	v_mov_b32_e32 v5, v72
	s_waitcnt lgkmcnt(3)
	v_mov_b32_e32 v166, v164
	s_waitcnt lgkmcnt(2)
	v_mov_b32_e32 v167, v168
	v_pk_mul_f32 v[212:213], v[4:5], v[166:167]
	v_mov_b32_e32 v166, v71
	v_mov_b32_e32 v167, v73
	v_mov_b32_e32 v168, v165
	v_pk_mul_f32 v[214:215], v[166:167], v[168:169]
	v_mov_b32_e32 v164, v74
	v_mov_b32_e32 v165, v76
	s_waitcnt lgkmcnt(1)
	v_mov_b32_e32 v168, v170
	s_waitcnt lgkmcnt(0)
	v_mov_b32_e32 v169, v210
	v_pk_mul_f32 v[216:217], v[164:165], v[168:169]
	v_mov_b32_e32 v168, v75
	v_mov_b32_e32 v169, v77
	v_mov_b32_e32 v210, v171
	v_pk_mul_f32 v[170:171], v[168:169], v[210:211]
	v_bfe_u32 v211, v215, 16, 1
	v_bfe_u32 v209, v171, 16, 1
	v_bfe_u32 v218, v214, 16, 1
	v_add3_u32 v211, v215, v211, s55
	v_bfe_u32 v215, v216, 16, 1
	v_bfe_u32 v210, v170, 16, 1
	v_add3_u32 v214, v214, v218, s55
	v_add3_u32 v171, v171, v209, s55
	v_bfe_u32 v209, v212, 16, 1
	v_bfe_u32 v218, v217, 16, 1
	v_add3_u32 v215, v216, v215, s55
	v_add3_u32 v170, v170, v210, s55
	v_bfe_u32 v210, v213, 16, 1
	v_add3_u32 v217, v217, v218, s55
	v_add3_u32 v209, v212, v209, s55
	v_lshrrev_b32_e32 v212, 16, v215
	v_add3_u32 v210, v213, v210, s55
	v_lshrrev_b32_e32 v213, 16, v217
	v_and_or_b32 v212, v170, s56, v212
	v_or_b32_e32 v170, v207, v184
	v_and_or_b32 v213, v171, s56, v213
	v_and_or_b32 v171, v170, s57, v208
	v_cmp_eq_u32_e64 s[4:5], 0, v172
	v_lshrrev_b32_e32 v209, 16, v209
	v_lshrrev_b32_e32 v210, 16, v210
	v_cndmask_b32_e64 v170, v171, v170, s[4:5]
	v_add_u32_e32 v170, v170, v173
	v_and_or_b32 v211, v211, s56, v210
	v_and_or_b32 v210, v214, s56, v209
	v_ashrrev_i32_e32 v209, 31, v170
	v_mad_u64_u32 v[170:171], s[0:1], v170, v153, 0
	v_mov_b32_e32 v214, v171
	v_mad_u64_u32 v[214:215], s[0:1], v209, v153, v[214:215]
	v_ashrrev_i32_e32 v163, 31, v162
	v_mov_b32_e32 v171, v214
	v_lshl_add_u64 v[214:215], v[170:171], 1, v[154:155]
	v_lshlrev_b64 v[170:171], 1, v[162:163]
	v_lshl_add_u64 v[214:215], v[214:215], 0, v[170:171]
	v_lshlrev_b64 v[162:163], 1, v[158:159]
	v_lshl_add_u64 v[214:215], v[214:215], 0, v[162:163]
	ds_read2st64_b32 v[216:217], v187 offset1:1
	ds_read2st64_b32 v[218:219], v187 offset0:2 offset1:3
	global_store_dwordx4 v[214:215], v[210:213], off nt
	ds_read2st64_b32 v[210:211], v187 offset0:4 offset1:5
	ds_read2st64_b32 v[212:213], v187 offset0:6 offset1:7
	s_waitcnt lgkmcnt(3)
	v_mov_b32_e32 v214, v216
	s_waitcnt lgkmcnt(2)
	v_mov_b32_e32 v215, v218
	v_mov_b32_e32 v218, v217
	v_pk_mul_f32 v[216:217], v[166:167], v[218:219]
	s_waitcnt lgkmcnt(0)
	v_mov_b32_e32 v219, v212
	v_mov_b32_e32 v212, v211
	v_mov_b32_e32 v218, v210
	v_pk_mul_f32 v[210:211], v[168:169], v[212:213]
	v_pk_mul_f32 v[214:215], v[4:5], v[214:215]
	v_pk_mul_f32 v[218:219], v[164:165], v[218:219]
	v_bfe_u32 v209, v211, 16, 1
	v_bfe_u32 v212, v210, 16, 1
	v_bfe_u32 v213, v217, 16, 1
	v_bfe_u32 v220, v216, 16, 1
	v_add3_u32 v216, v216, v220, s55
	v_add3_u32 v217, v217, v213, s55
	v_add3_u32 v210, v210, v212, s55
	v_add3_u32 v209, v211, v209, s55
	v_bfe_u32 v211, v214, 16, 1
	v_bfe_u32 v212, v215, 16, 1
	v_bfe_u32 v213, v218, 16, 1
	v_bfe_u32 v220, v219, 16, 1
	v_add3_u32 v219, v219, v220, s55
	v_add3_u32 v213, v218, v213, s55
	v_add3_u32 v212, v215, v212, s55
	v_add3_u32 v211, v214, v211, s55
	v_lshrrev_b32_e32 v214, 16, v211
	v_lshrrev_b32_e32 v211, 16, v212
	v_lshrrev_b32_e32 v212, 16, v213
	v_lshrrev_b32_e32 v213, 16, v219
	v_and_or_b32 v213, v209, s56, v213
	v_or_b32_e32 v209, v207, v186
	v_and_or_b32 v212, v210, s56, v212
	v_and_or_b32 v210, v216, s56, v214
	v_and_or_b32 v214, v209, s62, v208
	v_cndmask_b32_e64 v209, v214, v209, s[4:5]
	v_add_u32_e32 v209, v209, v173
	v_mad_u64_u32 v[214:215], s[0:1], v209, v153, 0
	v_and_or_b32 v211, v217, s56, v211
	v_ashrrev_i32_e32 v217, 31, v209
	v_mov_b32_e32 v216, v215
	v_mad_u64_u32 v[216:217], s[0:1], v217, v153, v[216:217]
	v_mov_b32_e32 v215, v216
	v_lshl_add_u64 v[214:215], v[214:215], 1, v[154:155]
	v_lshl_add_u64 v[214:215], v[214:215], 0, v[170:171]
	v_lshl_add_u64 v[214:215], v[214:215], 0, v[162:163]
	ds_read2st64_b32 v[216:217], v189 offset1:1
	ds_read2st64_b32 v[218:219], v189 offset0:2 offset1:3
	global_store_dwordx4 v[214:215], v[210:213], off nt
	ds_read2st64_b32 v[210:211], v189 offset0:4 offset1:5
	ds_read2st64_b32 v[212:213], v189 offset0:6 offset1:7
	s_waitcnt lgkmcnt(3)
	v_mov_b32_e32 v214, v216
	s_waitcnt lgkmcnt(2)
	v_mov_b32_e32 v215, v218
	v_mov_b32_e32 v218, v217
	v_pk_mul_f32 v[216:217], v[166:167], v[218:219]
	s_waitcnt lgkmcnt(0)
; #define LAS __attribute__((address_space(3)))
; __device__ __forceinline__ unsigned pk2(float lo, float hi) { return f2bf(lo) | (f2bf(hi) << 16); }
; __device__ __forceinline__ void cv_process(const CvDesc& d, int lane, const f32x4 (&v)[16], const f32x4& g0, const f32x4& g1, LAS float* scr) {
;     ...
;     for (int j = 0; j < 8; ++j) { const int n = (lane >> 3) + 8 * j; const LAS float* s = scr + (8 * c) * 64 + (n ^ (8 * c));
;         u32x4 o; o.x = pk2(s[0 * 64] * g0[0], s[1 * 64] * g0[1]); o.y = pk2(s[2 * 64] * g0[2], s[3 * 64] * g0[3]); o.z = pk2(s[4 * 64] * g1[0], s[5 * 64] * g1[1]); o.w = pk2(s[6 * 64] * g1[2], s[7 * 64] * g1[3]);
;         const int ng = n0 + n, drow = d.mode ? (((ng >> 7) << 8) + (ng & 127) + d.off) : (d.off + ng);
;         *(u32x4*)(d.dst + (size_t)drow * d.K + k0 + 8 * c) = o; }
	v_mov_b32_e32 v219, v212
	v_mov_b32_e32 v212, v211
	v_mov_b32_e32 v218, v210
	v_pk_mul_f32 v[210:211], v[168:169], v[212:213]
	v_pk_mul_f32 v[214:215], v[4:5], v[214:215]
	v_pk_mul_f32 v[218:219], v[164:165], v[218:219]
	v_bfe_u32 v209, v211, 16, 1
	v_bfe_u32 v212, v210, 16, 1
	v_bfe_u32 v213, v217, 16, 1
	v_bfe_u32 v220, v216, 16, 1
	v_add3_u32 v216, v216, v220, s55
	v_add3_u32 v217, v217, v213, s55
	v_add3_u32 v210, v210, v212, s55
	v_add3_u32 v209, v211, v209, s55
	v_bfe_u32 v211, v214, 16, 1
	v_bfe_u32 v212, v215, 16, 1
	v_bfe_u32 v213, v218, 16, 1
	v_bfe_u32 v220, v219, 16, 1
	v_add3_u32 v219, v219, v220, s55
	v_add3_u32 v213, v218, v213, s55
	v_add3_u32 v212, v215, v212, s55
	v_add3_u32 v211, v214, v211, s55
	v_lshrrev_b32_e32 v214, 16, v211
	v_lshrrev_b32_e32 v211, 16, v212
	v_lshrrev_b32_e32 v212, 16, v213
	v_lshrrev_b32_e32 v213, 16, v219
	v_and_or_b32 v213, v209, s56, v213
	v_or_b32_e32 v209, v207, v188
	v_and_or_b32 v212, v210, s56, v212
	v_and_or_b32 v210, v216, s56, v214
	v_and_or_b32 v214, v209, s63, v208
	v_cndmask_b32_e64 v209, v214, v209, s[4:5]
	v_add_u32_e32 v209, v209, v173
	v_mad_u64_u32 v[214:215], s[0:1], v209, v153, 0
	v_and_or_b32 v211, v217, s56, v211
	v_ashrrev_i32_e32 v217, 31, v209
	v_mov_b32_e32 v216, v215
	v_mad_u64_u32 v[216:217], s[0:1], v217, v153, v[216:217]
	v_mov_b32_e32 v215, v216
	v_lshl_add_u64 v[214:215], v[214:215], 1, v[154:155]
	v_lshl_add_u64 v[214:215], v[214:215], 0, v[170:171]
	v_lshl_add_u64 v[214:215], v[214:215], 0, v[162:163]
	ds_read2st64_b32 v[216:217], v191 offset1:1
	ds_read2st64_b32 v[218:219], v191 offset0:2 offset1:3
	global_store_dwordx4 v[214:215], v[210:213], off nt
	ds_read2st64_b32 v[210:211], v191 offset0:4 offset1:5
	ds_read2st64_b32 v[212:213], v191 offset0:6 offset1:7
	s_waitcnt lgkmcnt(3)
	v_mov_b32_e32 v214, v216
	s_waitcnt lgkmcnt(2)
	v_mov_b32_e32 v215, v218
	v_mov_b32_e32 v218, v217
	v_pk_mul_f32 v[216:217], v[166:167], v[218:219]
	s_waitcnt lgkmcnt(0)
	v_mov_b32_e32 v219, v212
	v_mov_b32_e32 v212, v211
	v_mov_b32_e32 v218, v210
	v_pk_mul_f32 v[210:211], v[168:169], v[212:213]
	v_pk_mul_f32 v[214:215], v[4:5], v[214:215]
	v_pk_mul_f32 v[218:219], v[164:165], v[218:219]
	v_bfe_u32 v209, v211, 16, 1
	v_bfe_u32 v212, v210, 16, 1
	v_bfe_u32 v213, v217, 16, 1
	v_bfe_u32 v220, v216, 16, 1
	v_add3_u32 v216, v216, v220, s55
	v_add3_u32 v217, v217, v213, s55
	v_add3_u32 v210, v210, v212, s55
	v_add3_u32 v209, v211, v209, s55
	v_bfe_u32 v211, v214, 16, 1
	v_bfe_u32 v212, v215, 16, 1
	v_bfe_u32 v213, v218, 16, 1
	v_bfe_u32 v220, v219, 16, 1
	v_add3_u32 v219, v219, v220, s55
	v_add3_u32 v213, v218, v213, s55
	v_add3_u32 v212, v215, v212, s55
	v_add3_u32 v211, v214, v211, s55
	v_lshrrev_b32_e32 v214, 16, v211
	v_lshrrev_b32_e32 v211, 16, v212
	v_lshrrev_b32_e32 v212, 16, v213
	v_lshrrev_b32_e32 v213, 16, v219
	v_and_or_b32 v213, v209, s56, v213
	v_or_b32_e32 v209, v207, v190
	v_and_or_b32 v212, v210, s56, v212
	v_and_or_b32 v210, v216, s56, v214
	v_and_or_b32 v214, v209, s64, v208
	v_cndmask_b32_e64 v209, v214, v209, s[4:5]
	v_add_u32_e32 v209, v209, v173
	v_mad_u64_u32 v[214:215], s[0:1], v209, v153, 0
	v_and_or_b32 v211, v217, s56, v211
	v_ashrrev_i32_e32 v217, 31, v209
	v_mov_b32_e32 v216, v215
	v_mad_u64_u32 v[216:217], s[0:1], v217, v153, v[216:217]
	v_mov_b32_e32 v215, v216
	v_lshl_add_u64 v[214:215], v[214:215], 1, v[154:155]
	v_lshl_add_u64 v[214:215], v[214:215], 0, v[170:171]
	v_lshl_add_u64 v[214:215], v[214:215], 0, v[162:163]
	ds_read2st64_b32 v[216:217], v193 offset1:1
	ds_read2st64_b32 v[218:219], v193 offset0:2 offset1:3
	global_store_dwordx4 v[214:215], v[210:213], off nt
	ds_read2st64_b32 v[210:211], v193 offset0:4 offset1:5
	ds_read2st64_b32 v[212:213], v193 offset0:6 offset1:7
	s_waitcnt lgkmcnt(3)
	v_mov_b32_e32 v214, v216
	s_waitcnt lgkmcnt(2)
	v_mov_b32_e32 v215, v218
	v_mov_b32_e32 v218, v217
	v_pk_mul_f32 v[216:217], v[166:167], v[218:219]
	s_waitcnt lgkmcnt(0)
	v_mov_b32_e32 v219, v212
	v_mov_b32_e32 v212, v211
	v_mov_b32_e32 v218, v210
	v_pk_mul_f32 v[210:211], v[168:169], v[212:213]
	v_pk_mul_f32 v[214:215], v[4:5], v[214:215]
	v_pk_mul_f32 v[218:219], v[164:165], v[218:219]
	v_bfe_u32 v209, v211, 16, 1
	v_bfe_u32 v212, v210, 16, 1
	v_bfe_u32 v213, v217, 16, 1
	v_bfe_u32 v220, v216, 16, 1
	v_add3_u32 v216, v216, v220, s55
	v_add3_u32 v217, v217, v213, s55
	v_add3_u32 v210, v210, v212, s55
	v_add3_u32 v209, v211, v209, s55
	v_bfe_u32 v211, v214, 16, 1
	v_bfe_u32 v212, v215, 16, 1
	v_bfe_u32 v213, v218, 16, 1
	v_bfe_u32 v220, v219, 16, 1
	v_add3_u32 v219, v219, v220, s55
	v_add3_u32 v213, v218, v213, s55
	v_add3_u32 v212, v215, v212, s55
	v_add3_u32 v211, v214, v211, s55
	v_lshrrev_b32_e32 v214, 16, v211
	v_lshrrev_b32_e32 v211, 16, v212
	v_lshrrev_b32_e32 v212, 16, v213
	v_lshrrev_b32_e32 v213, 16, v219
	v_and_or_b32 v213, v209, s56, v213
	v_or_b32_e32 v209, v207, v192
	v_and_or_b32 v212, v210, s56, v212
	v_and_or_b32 v210, v216, s56, v214
	v_and_or_b32 v214, v209, s65, v208
	v_cndmask_b32_e64 v209, v214, v209, s[4:5]
	v_add_u32_e32 v209, v209, v173
	v_mad_u64_u32 v[214:215], s[0:1], v209, v153, 0
	v_and_or_b32 v211, v217, s56, v211
	v_ashrrev_i32_e32 v217, 31, v209
	v_mov_b32_e32 v216, v215
	v_mad_u64_u32 v[216:217], s[0:1], v217, v153, v[216:217]
	v_mov_b32_e32 v215, v216
	v_lshl_add_u64 v[214:215], v[214:215], 1, v[154:155]
	v_lshl_add_u64 v[214:215], v[214:215], 0, v[170:171]
	v_lshl_add_u64 v[214:215], v[214:215], 0, v[162:163]
	ds_read2st64_b32 v[216:217], v195 offset1:1
	ds_read2st64_b32 v[218:219], v195 offset0:2 offset1:3
	global_store_dwordx4 v[214:215], v[210:213], off nt
	ds_read2st64_b32 v[210:211], v195 offset0:4 offset1:5
	ds_read2st64_b32 v[212:213], v195 offset0:6 offset1:7
	s_waitcnt lgkmcnt(3)
; #define LAS __attribute__((address_space(3)))
; __device__ __forceinline__ unsigned pk2(float lo, float hi) { return f2bf(lo) | (f2bf(hi) << 16); }
; __device__ __forceinline__ void cv_process(const CvDesc& d, int lane, const f32x4 (&v)[16], const f32x4& g0, const f32x4& g1, LAS float* scr) {
;     ...
;     for (int j = 0; j < 8; ++j) { const int n = (lane >> 3) + 8 * j; const LAS float* s = scr + (8 * c) * 64 + (n ^ (8 * c));
;         u32x4 o; o.x = pk2(s[0 * 64] * g0[0], s[1 * 64] * g0[1]); o.y = pk2(s[2 * 64] * g0[2], s[3 * 64] * g0[3]); o.z = pk2(s[4 * 64] * g1[0], s[5 * 64] * g1[1]); o.w = pk2(s[6 * 64] * g1[2], s[7 * 64] * g1[3]);
;         const int ng = n0 + n, drow = d.mode ? (((ng >> 7) << 8) + (ng & 127) + d.off) : (d.off + ng);
;         *(u32x4*)(d.dst + (size_t)drow * d.K + k0 + 8 * c) = o; }
	v_mov_b32_e32 v214, v216
	s_waitcnt lgkmcnt(2)
	v_mov_b32_e32 v215, v218
	v_mov_b32_e32 v218, v217
	v_pk_mul_f32 v[216:217], v[166:167], v[218:219]
	s_waitcnt lgkmcnt(0)
	v_mov_b32_e32 v219, v212
	v_mov_b32_e32 v212, v211
	v_mov_b32_e32 v218, v210
	v_pk_mul_f32 v[210:211], v[168:169], v[212:213]
	v_pk_mul_f32 v[214:215], v[4:5], v[214:215]
	v_pk_mul_f32 v[218:219], v[164:165], v[218:219]
	v_bfe_u32 v209, v211, 16, 1
	v_bfe_u32 v212, v210, 16, 1
	v_bfe_u32 v213, v217, 16, 1
	v_bfe_u32 v220, v216, 16, 1
	v_add3_u32 v216, v216, v220, s55
	v_add3_u32 v217, v217, v213, s55
	v_add3_u32 v210, v210, v212, s55
	v_add3_u32 v209, v211, v209, s55
	v_bfe_u32 v211, v214, 16, 1
	v_bfe_u32 v212, v215, 16, 1
	v_bfe_u32 v213, v218, 16, 1
	v_bfe_u32 v220, v219, 16, 1
	v_add3_u32 v219, v219, v220, s55
	v_add3_u32 v213, v218, v213, s55
	v_add3_u32 v212, v215, v212, s55
	v_add3_u32 v211, v214, v211, s55
	v_lshrrev_b32_e32 v214, 16, v211
	v_lshrrev_b32_e32 v211, 16, v212
	v_lshrrev_b32_e32 v212, 16, v213
	v_lshrrev_b32_e32 v213, 16, v219
	v_and_or_b32 v213, v209, s56, v213
	v_or_b32_e32 v209, v207, v194
	v_and_or_b32 v212, v210, s56, v212
	v_and_or_b32 v210, v216, s56, v214
	v_and_or_b32 v214, v209, s66, v208
	v_cndmask_b32_e64 v209, v214, v209, s[4:5]
	v_add_u32_e32 v209, v209, v173
	v_mad_u64_u32 v[214:215], s[0:1], v209, v153, 0
	v_and_or_b32 v211, v217, s56, v211
	v_ashrrev_i32_e32 v217, 31, v209
	v_mov_b32_e32 v216, v215
	v_mad_u64_u32 v[216:217], s[0:1], v217, v153, v[216:217]
	v_mov_b32_e32 v215, v216
	v_lshl_add_u64 v[214:215], v[214:215], 1, v[154:155]
	v_lshl_add_u64 v[214:215], v[214:215], 0, v[170:171]
	v_lshl_add_u64 v[214:215], v[214:215], 0, v[162:163]
	ds_read2st64_b32 v[216:217], v197 offset1:1
	ds_read2st64_b32 v[218:219], v197 offset0:2 offset1:3
	global_store_dwordx4 v[214:215], v[210:213], off nt
	ds_read2st64_b32 v[210:211], v197 offset0:4 offset1:5
	ds_read2st64_b32 v[212:213], v197 offset0:6 offset1:7
	s_waitcnt lgkmcnt(3)
	v_mov_b32_e32 v214, v216
	s_waitcnt lgkmcnt(2)
	v_mov_b32_e32 v215, v218
	v_mov_b32_e32 v218, v217
	v_pk_mul_f32 v[216:217], v[166:167], v[218:219]
	s_waitcnt lgkmcnt(0)
	v_mov_b32_e32 v219, v212
	v_mov_b32_e32 v212, v211
	v_mov_b32_e32 v218, v210
	v_pk_mul_f32 v[210:211], v[168:169], v[212:213]
	v_pk_mul_f32 v[214:215], v[4:5], v[214:215]
	v_pk_mul_f32 v[218:219], v[164:165], v[218:219]
	v_bfe_u32 v209, v211, 16, 1
	v_bfe_u32 v212, v210, 16, 1
	v_bfe_u32 v213, v217, 16, 1
	v_bfe_u32 v220, v216, 16, 1
	v_add3_u32 v216, v216, v220, s55
	v_add3_u32 v217, v217, v213, s55
	v_add3_u32 v210, v210, v212, s55
	v_add3_u32 v209, v211, v209, s55
	v_bfe_u32 v211, v214, 16, 1
	v_bfe_u32 v212, v215, 16, 1
	v_bfe_u32 v213, v218, 16, 1
	v_bfe_u32 v220, v219, 16, 1
	v_add3_u32 v219, v219, v220, s55
	v_add3_u32 v213, v218, v213, s55
	v_add3_u32 v212, v215, v212, s55
	v_add3_u32 v211, v214, v211, s55
	v_lshrrev_b32_e32 v214, 16, v211
	v_lshrrev_b32_e32 v211, 16, v212
	v_lshrrev_b32_e32 v212, 16, v213
	v_lshrrev_b32_e32 v213, 16, v219
	v_and_or_b32 v213, v209, s56, v213
	v_or_b32_e32 v209, v207, v196
	v_and_or_b32 v212, v210, s56, v212
	v_and_or_b32 v210, v216, s56, v214
	v_and_or_b32 v214, v209, s67, v208
	v_cndmask_b32_e64 v209, v214, v209, s[4:5]
	v_add_u32_e32 v209, v209, v173
	v_mad_u64_u32 v[214:215], s[0:1], v209, v153, 0
	v_and_or_b32 v211, v217, s56, v211
	v_ashrrev_i32_e32 v217, 31, v209
	v_mov_b32_e32 v216, v215
	v_mad_u64_u32 v[216:217], s[0:1], v217, v153, v[216:217]
	v_mov_b32_e32 v215, v216
	v_lshl_add_u64 v[214:215], v[214:215], 1, v[154:155]
	v_lshl_add_u64 v[214:215], v[214:215], 0, v[170:171]
	v_lshl_add_u64 v[214:215], v[214:215], 0, v[162:163]
	global_store_dwordx4 v[214:215], v[210:213], off nt
	ds_read2st64_b32 v[210:211], v199 offset1:1
	ds_read2st64_b32 v[212:213], v199 offset0:2 offset1:3
	ds_read2st64_b32 v[214:215], v199 offset0:4 offset1:5
	ds_read2st64_b32 v[216:217], v199 offset0:6 offset1:7
	v_or_b32_e32 v207, v207, v198
	v_and_or_b32 v208, v207, s54, v208
	v_cndmask_b32_e64 v207, v208, v207, s[4:5]
	s_waitcnt lgkmcnt(3)
	v_mov_b32_e32 v208, v211
	s_waitcnt lgkmcnt(2)
	v_mov_b32_e32 v209, v213
	v_pk_mul_f32 v[166:167], v[166:167], v[208:209]
	s_waitcnt lgkmcnt(1)
	v_mov_b32_e32 v208, v215
	s_waitcnt lgkmcnt(0)
	v_mov_b32_e32 v209, v217
	v_mov_b32_e32 v211, v212
	v_pk_mul_f32 v[168:169], v[168:169], v[208:209]
	v_mov_b32_e32 v215, v216
	v_pk_mul_f32 v[4:5], v[4:5], v[210:211]
	v_pk_mul_f32 v[164:165], v[164:165], v[214:215]
	v_bfe_u32 v208, v169, 16, 1
	v_bfe_u32 v209, v168, 16, 1
	v_bfe_u32 v210, v167, 16, 1
	v_bfe_u32 v211, v166, 16, 1
	v_add3_u32 v211, v166, v211, s55
	v_add3_u32 v210, v167, v210, s55
	v_add3_u32 v166, v168, v209, s55
	v_add3_u32 v167, v169, v208, s55
	v_bfe_u32 v168, v4, 16, 1
	v_bfe_u32 v169, v5, 16, 1
	v_bfe_u32 v208, v164, 16, 1
	v_bfe_u32 v209, v165, 16, 1
	v_add3_u32 v165, v165, v209, s55
	v_add3_u32 v164, v164, v208, s55
	v_add3_u32 v5, v5, v169, s55
	v_add3_u32 v4, v4, v168, s55
	v_add_u32_e32 v207, v207, v173
	v_lshrrev_b32_e32 v4, 16, v4
	v_lshrrev_b32_e32 v5, 16, v5
	v_lshrrev_b32_e32 v164, 16, v164
	v_lshrrev_b32_e32 v165, 16, v165
	v_and_or_b32 v167, v167, s56, v165
	v_and_or_b32 v166, v166, s56, v164
	v_and_or_b32 v165, v210, s56, v5
	v_and_or_b32 v164, v211, s56, v4
	v_mad_u64_u32 v[4:5], s[0:1], v207, v153, 0
	v_ashrrev_i32_e32 v169, 31, v207
	v_mov_b32_e32 v168, v5
	v_mad_u64_u32 v[168:169], s[0:1], v169, v153, v[168:169]
	v_mov_b32_e32 v5, v168
	v_lshl_add_u64 v[4:5], v[4:5], 1, v[154:155]
	v_lshl_add_u64 v[4:5], v[4:5], 0, v[170:171]
	v_lshl_add_u64 v[4:5], v[4:5], 0, v[162:163]
	global_store_dwordx4 v[4:5], v[164:167], off nt
	s_waitcnt lgkmcnt(0)
	s_mov_b64 s[0:1], 0
	s_and_saveexec_b64 s[36:37], vcc
	s_cbranch_execz .LBB0_142
; #define JOB(CNT, SRC, KK, NN, DST, GAIN, MODE, OFF) if (!hit) { if (r < (CNT)) { d.src = (SRC); d.K = (KK); d.N = (NN); d.dst = (bf16*)(DST); d.gain = (GAIN); d.mode = (MODE); d.off = (OFF); d.r = r; hit = true; } else r -= (CNT); }
; #define PLE_JOBS(L) \
;     JOB(CV_DD, a.in[12] + (size_t)(L) * D * D, D, D, ws + WS_WG + (size_t)(L) * SZ_WG, a.in[11] + (L) * D, 0, 0) \
;     JOB(CV_PJ, a.in[13] + (size_t)(L) * PLE * D, PLE, D, ws + WS_WP + (size_t)(L) * SZ_WP, nullptr, 0, 0)
; __device__ __forceinline__ CvDesc cv_decode(const Args& a, int it) {
;     ...
;     int r = it; CvDesc d; d.src = nullptr; d.dst = nullptr; d.gain = nullptr; d.K = 64; d.N = 64; d.mode = 0; d.off = 0; d.r = 0; bool hit = false;
;     ...
;     FFN_JOBS(0, 0, 3, 4, 5, 2) FFN_JOBS(1, 0, 8, 9, 10, 7) PLE_JOBS(0)
;     FFN_JOBS(0, 1, 3, 4, 5, 2)
;     JOB(CV_IN, a.in[14], D, 2 * GW, ws + WS_WIN, a.in[6], 0, 0)
;     JOB(CV_OUT, a.in[19], GW, D, ws + WS_WOUT, nullptr, 0, 0)
;     JOB(CV_DD, a.in[20], D, D, ws + WS_WQKV, a.in[6] + D, 0, 0)
;     JOB(CV_KV, a.in[22], D, 256, ws + WS_WQKV, a.in[6] + D, 0, 2048)
;     JOB(CV_KV, a.in[24], D, 256, ws + WS_WQKV, a.in[6] + D, 0, 2304)
;     FFN_JOBS(1, 1, 8, 9, 10, 7) PLE_JOBS(1)
	s_mov_b32 s99, 0
	v_add_u32_e32 v168, s42, v206
	v_cmp_gt_i32_e32 vcc, s3, v168
	s_and_saveexec_b64 s[38:39], vcc
	s_cbranch_execz .LBB0_141
	s_mov_b32 s99, 1
	v_cmp_lt_i32_e64 s[4:5], s43, v168
	v_mov_b32_e32 v172, 1
	v_mov_b32_e32 v153, 0x800
	v_mov_b32_e32 v151, 0x1600
	v_mov_b64_e32 v[164:165], s[8:9]
	v_mov_b64_e32 v[154:155], s[44:45]
	v_mov_b64_e32 v[4:5], s[10:11]
	v_mov_b32_e32 v174, v168
	v_mov_b32_e32 v3, v168
	s_and_saveexec_b64 s[0:1], s[4:5]
	v_add_u32_e32 v3, 0xfffff500, v168
	v_mov_b32_e32 v172, 0
	v_mov_b64_e32 v[164:165], 0
	v_mov_b32_e32 v151, 64
	v_mov_b32_e32 v153, 64
	v_mov_b64_e32 v[154:155], 0
	v_mov_b64_e32 v[4:5], 0
	v_mov_b32_e32 v174, 0
	s_or_b64 exec, exec, s[0:1]
	s_mov_b64 s[46:47], -1
	v_mov_b32_e32 v173, 0
	s_mov_b64 s[50:51], -1
	s_and_saveexec_b64 s[0:1], s[4:5]
	s_cbranch_execz .LBB0_239
	v_cmp_lt_i32_e64 s[4:5], s43, v3
	v_mov_b32_e32 v15, 0x1600
	v_mov_b32_e32 v14, 0x800
	v_mov_b32_e32 v12, 1
	v_mov_b32_e32 v173, 0x80
	v_mov_b64_e32 v[6:7], s[12:13]
	v_mov_b64_e32 v[8:9], s[44:45]
	v_mov_b64_e32 v[10:11], s[8:9]
	v_mov_b32_e32 v13, v3
	s_and_saveexec_b64 s[52:53], s[4:5]
	s_cbranch_execz .LBB0_238
	v_add_u32_e32 v3, 0xfffff500, v3
	v_mov_b32_e32 v173, 0
	s_xor_b64 s[50:51], exec, -1
	v_mov_b32_e32 v13, v174
	v_mov_b32_e32 v12, v172
	v_mov_b64_e32 v[6:7], v[4:5]
	v_mov_b64_e32 v[8:9], v[154:155]
	v_mov_b64_e32 v[10:11], v[164:165]
	v_mov_b32_e32 v14, v153
	v_mov_b32_e32 v15, v151

; __device__ __forceinline__ unsigned pk2(float lo, float hi) { return f2bf(lo) | (f2bf(hi) << 16); }
; __device__ __forceinline__ void p0_prologue(const Args& a, LAS unsigned char* lds) {
;     ...
;       for (int m = gw; m < M; m += NGW) { const f32x4* xr = (const f32x4*)(x + (size_t)m * D) + lane; u32x2* o8 = (u32x2*)(xb + (size_t)(m >> 8) * 8 * 65536 + (size_t)(m & 255) * 256) + lane; float s = 0.f;
; #pragma unroll
;           for (int j = 0; j < 8; ++j) { const f32x4 v = __builtin_nontemporal_load(xr + 64 * j); s += (v[0] * v[0] + v[1] * v[1]) + (v[2] * v[2] + v[3] * v[3]); u32x2 w; w.x = pk2(v[0], v[1]); w.y = pk2(v[2], v[3]); o8[(size_t)j * (65536 / 4)] = w; }
.Lxcv_last:
	s_waitcnt vmcnt(15)
	v_and_b32_sdwa v5, v27, v22 dst_sel:DWORD dst_unused:UNUSED_PAD src0_sel:WORD_1 src1_sel:DWORD
	v_and_b32_sdwa v7, v25, v22 dst_sel:DWORD dst_unused:UNUSED_PAD src0_sel:WORD_1 src1_sel:DWORD
	v_and_b32_sdwa v6, v26, v22 dst_sel:DWORD dst_unused:UNUSED_PAD src0_sel:WORD_1 src1_sel:DWORD
	v_and_b32_sdwa v23, v24, v22 dst_sel:DWORD dst_unused:UNUSED_PAD src0_sel:WORD_1 src1_sel:DWORD
	v_add3_u32 v5, v27, v5, s18
	v_add3_u32 v7, v25, v7, s18
	v_add3_u32 v23, v24, v23, s18
	v_add3_u32 v6, v26, v6, s18
	v_and_b32_e32 v5, 0xffff0000, v5
	v_and_b32_e32 v7, 0xffff0000, v7
	v_or_b32_sdwa v65, v5, v6 dst_sel:DWORD dst_unused:UNUSED_PAD src0_sel:DWORD src1_sel:WORD_1
	v_or_b32_sdwa v64, v7, v23 dst_sel:DWORD dst_unused:UNUSED_PAD src0_sel:DWORD src1_sel:WORD_1
	v_mul_f32_e32 v3, v25, v25
	v_mul_f32_e32 v4, v27, v27
	global_store_dwordx2 v11, v[64:65], s[12:13] nt
	v_fmac_f32_e32 v3, v24, v24
	v_fmac_f32_e32 v4, v26, v26
	v_add_f32_e32 v2, v3, v4
	s_mov_b64 exec, s[20:21]
	global_load_dwordx4 v[24:27], v10, s[14:15] offset:-4096 nt
	s_mov_b64 exec, s[22:23]
	s_waitcnt vmcnt(14)
	v_and_b32_sdwa v5, v31, v22 dst_sel:DWORD dst_unused:UNUSED_PAD src0_sel:WORD_1 src1_sel:DWORD
	v_and_b32_sdwa v7, v29, v22 dst_sel:DWORD dst_unused:UNUSED_PAD src0_sel:WORD_1 src1_sel:DWORD
	v_and_b32_sdwa v6, v30, v22 dst_sel:DWORD dst_unused:UNUSED_PAD src0_sel:WORD_1 src1_sel:DWORD
	v_and_b32_sdwa v23, v28, v22 dst_sel:DWORD dst_unused:UNUSED_PAD src0_sel:WORD_1 src1_sel:DWORD
	v_add3_u32 v5, v31, v5, s18
	v_add3_u32 v7, v29, v7, s18
	v_add3_u32 v23, v28, v23, s18
	v_add3_u32 v6, v30, v6, s18
	v_and_b32_e32 v5, 0xffff0000, v5
	v_and_b32_e32 v7, 0xffff0000, v7
	s_add_u32 s24, s12, 0x20000
	s_addc_u32 s25, s13, 0
	v_or_b32_sdwa v67, v5, v6 dst_sel:DWORD dst_unused:UNUSED_PAD src0_sel:DWORD src1_sel:WORD_1
	v_or_b32_sdwa v66, v7, v23 dst_sel:DWORD dst_unused:UNUSED_PAD src0_sel:DWORD src1_sel:WORD_1
	v_mul_f32_e32 v3, v29, v29
	v_mul_f32_e32 v4, v31, v31
	global_store_dwordx2 v11, v[66:67], s[24:25] nt
	v_fmac_f32_e32 v3, v28, v28
	v_fmac_f32_e32 v4, v30, v30
	v_add_f32_e32 v3, v3, v4
	v_add_f32_e32 v2, v2, v3
	s_mov_b64 exec, s[20:21]
	global_load_dwordx4 v[28:31], v10, s[14:15] offset:-3072 nt
	s_mov_b64 exec, s[22:23]
	s_waitcnt vmcnt(13)
	v_and_b32_sdwa v5, v35, v22 dst_sel:DWORD dst_unused:UNUSED_PAD src0_sel:WORD_1 src1_sel:DWORD
	v_and_b32_sdwa v7, v33, v22 dst_sel:DWORD dst_unused:UNUSED_PAD src0_sel:WORD_1 src1_sel:DWORD
	v_and_b32_sdwa v6, v34, v22 dst_sel:DWORD dst_unused:UNUSED_PAD src0_sel:WORD_1 src1_sel:DWORD
	v_and_b32_sdwa v23, v32, v22 dst_sel:DWORD dst_unused:UNUSED_PAD src0_sel:WORD_1 src1_sel:DWORD
	v_add3_u32 v5, v35, v5, s18
	v_add3_u32 v7, v33, v7, s18
	v_add3_u32 v23, v32, v23, s18
	v_add3_u32 v6, v34, v6, s18
	v_and_b32_e32 v5, 0xffff0000, v5
	v_and_b32_e32 v7, 0xffff0000, v7
	s_add_u32 s24, s12, 0x40000
	s_addc_u32 s25, s13, 0
	v_or_b32_sdwa v69, v5, v6 dst_sel:DWORD dst_unused:UNUSED_PAD src0_sel:DWORD src1_sel:WORD_1
	v_or_b32_sdwa v68, v7, v23 dst_sel:DWORD dst_unused:UNUSED_PAD src0_sel:DWORD src1_sel:WORD_1
	v_mul_f32_e32 v3, v33, v33
	v_mul_f32_e32 v4, v35, v35
	global_store_dwordx2 v11, v[68:69], s[24:25] nt
	v_fmac_f32_e32 v3, v32, v32
	v_fmac_f32_e32 v4, v34, v34
	v_add_f32_e32 v3, v3, v4
	v_add_f32_e32 v2, v2, v3
	s_mov_b64 exec, s[20:21]
	global_load_dwordx4 v[32:35], v10, s[14:15] offset:-2048 nt
	s_mov_b64 exec, s[22:23]
	s_waitcnt vmcnt(12)
	v_and_b32_sdwa v5, v39, v22 dst_sel:DWORD dst_unused:UNUSED_PAD src0_sel:WORD_1 src1_sel:DWORD
	v_and_b32_sdwa v7, v37, v22 dst_sel:DWORD dst_unused:UNUSED_PAD src0_sel:WORD_1 src1_sel:DWORD
	v_and_b32_sdwa v6, v38, v22 dst_sel:DWORD dst_unused:UNUSED_PAD src0_sel:WORD_1 src1_sel:DWORD
	v_and_b32_sdwa v23, v36, v22 dst_sel:DWORD dst_unused:UNUSED_PAD src0_sel:WORD_1 src1_sel:DWORD
	v_add3_u32 v5, v39, v5, s18
	v_add3_u32 v7, v37, v7, s18
	v_add3_u32 v23, v36, v23, s18
	v_add3_u32 v6, v38, v6, s18
	v_and_b32_e32 v5, 0xffff0000, v5
	v_and_b32_e32 v7, 0xffff0000, v7
	s_add_u32 s24, s12, 0x60000
	s_addc_u32 s25, s13, 0
	v_or_b32_sdwa v71, v5, v6 dst_sel:DWORD dst_unused:UNUSED_PAD src0_sel:DWORD src1_sel:WORD_1
	v_or_b32_sdwa v70, v7, v23 dst_sel:DWORD dst_unused:UNUSED_PAD src0_sel:DWORD src1_sel:WORD_1
	v_mul_f32_e32 v3, v37, v37
	v_mul_f32_e32 v4, v39, v39
	global_store_dwordx2 v11, v[70:71], s[24:25] nt
	v_fmac_f32_e32 v3, v36, v36
	v_fmac_f32_e32 v4, v38, v38
	v_add_f32_e32 v3, v3, v4
	v_add_f32_e32 v2, v2, v3
	s_mov_b64 exec, s[20:21]
	global_load_dwordx4 v[36:39], v10, s[14:15] offset:-1024 nt
	s_mov_b64 exec, s[22:23]
	s_waitcnt vmcnt(11)
	v_and_b32_sdwa v5, v43, v22 dst_sel:DWORD dst_unused:UNUSED_PAD src0_sel:WORD_1 src1_sel:DWORD
	v_and_b32_sdwa v7, v41, v22 dst_sel:DWORD dst_unused:UNUSED_PAD src0_sel:WORD_1 src1_sel:DWORD
	v_and_b32_sdwa v6, v42, v22 dst_sel:DWORD dst_unused:UNUSED_PAD src0_sel:WORD_1 src1_sel:DWORD
	v_and_b32_sdwa v23, v40, v22 dst_sel:DWORD dst_unused:UNUSED_PAD src0_sel:WORD_1 src1_sel:DWORD
	v_add3_u32 v5, v43, v5, s18
	v_add3_u32 v7, v41, v7, s18
	v_add3_u32 v23, v40, v23, s18
	v_add3_u32 v6, v42, v6, s18
	v_and_b32_e32 v5, 0xffff0000, v5
	v_and_b32_e32 v7, 0xffff0000, v7
	s_add_u32 s24, s12, 0x80000
	s_addc_u32 s25, s13, 0
	v_or_b32_sdwa v73, v5, v6 dst_sel:DWORD dst_unused:UNUSED_PAD src0_sel:DWORD src1_sel:WORD_1
	v_or_b32_sdwa v72, v7, v23 dst_sel:DWORD dst_unused:UNUSED_PAD src0_sel:DWORD src1_sel:WORD_1
	v_mul_f32_e32 v3, v41, v41
	v_mul_f32_e32 v4, v43, v43
	global_store_dwordx2 v11, v[72:73], s[24:25] nt
	v_fmac_f32_e32 v3, v40, v40
	v_fmac_f32_e32 v4, v42, v42
	v_add_f32_e32 v3, v3, v4
	v_add_f32_e32 v2, v2, v3
	s_mov_b64 exec, s[20:21]
	global_load_dwordx4 v[40:43], v10, s[14:15] offset:0 nt
	s_mov_b64 exec, s[22:23]
	s_waitcnt vmcnt(10)
; __device__ __forceinline__ unsigned pk2(float lo, float hi) { return f2bf(lo) | (f2bf(hi) << 16); }
; __device__ __forceinline__ void p0_prologue(const Args& a, LAS unsigned char* lds) {
;     ...
;       for (int m = gw; m < M; m += NGW) { const f32x4* xr = (const f32x4*)(x + (size_t)m * D) + lane; u32x2* o8 = (u32x2*)(xb + (size_t)(m >> 8) * 8 * 65536 + (size_t)(m & 255) * 256) + lane; float s = 0.f;
; #pragma unroll
;           for (int j = 0; j < 8; ++j) { const f32x4 v = __builtin_nontemporal_load(xr + 64 * j); s += (v[0] * v[0] + v[1] * v[1]) + (v[2] * v[2] + v[3] * v[3]); u32x2 w; w.x = pk2(v[0], v[1]); w.y = pk2(v[2], v[3]); o8[(size_t)j * (65536 / 4)] = w; }
	v_and_b32_sdwa v5, v47, v22 dst_sel:DWORD dst_unused:UNUSED_PAD src0_sel:WORD_1 src1_sel:DWORD
	v_and_b32_sdwa v7, v45, v22 dst_sel:DWORD dst_unused:UNUSED_PAD src0_sel:WORD_1 src1_sel:DWORD
	v_and_b32_sdwa v6, v46, v22 dst_sel:DWORD dst_unused:UNUSED_PAD src0_sel:WORD_1 src1_sel:DWORD
	v_and_b32_sdwa v23, v44, v22 dst_sel:DWORD dst_unused:UNUSED_PAD src0_sel:WORD_1 src1_sel:DWORD
	v_add3_u32 v5, v47, v5, s18
	v_add3_u32 v7, v45, v7, s18
	v_add3_u32 v23, v44, v23, s18
	v_add3_u32 v6, v46, v6, s18
	v_and_b32_e32 v5, 0xffff0000, v5
	v_and_b32_e32 v7, 0xffff0000, v7
	s_add_u32 s24, s12, 0xa0000
	s_addc_u32 s25, s13, 0
	v_or_b32_sdwa v75, v5, v6 dst_sel:DWORD dst_unused:UNUSED_PAD src0_sel:DWORD src1_sel:WORD_1
	v_or_b32_sdwa v74, v7, v23 dst_sel:DWORD dst_unused:UNUSED_PAD src0_sel:DWORD src1_sel:WORD_1
	v_mul_f32_e32 v3, v45, v45
	v_mul_f32_e32 v4, v47, v47
	global_store_dwordx2 v11, v[74:75], s[24:25] nt
	v_fmac_f32_e32 v3, v44, v44
	v_fmac_f32_e32 v4, v46, v46
	v_add_f32_e32 v3, v3, v4
	v_add_f32_e32 v2, v2, v3
	s_mov_b64 exec, s[20:21]
	global_load_dwordx4 v[44:47], v10, s[14:15] offset:1024 nt
	s_mov_b64 exec, s[22:23]
	s_waitcnt vmcnt(9)
	v_and_b32_sdwa v5, v51, v22 dst_sel:DWORD dst_unused:UNUSED_PAD src0_sel:WORD_1 src1_sel:DWORD
	v_and_b32_sdwa v7, v49, v22 dst_sel:DWORD dst_unused:UNUSED_PAD src0_sel:WORD_1 src1_sel:DWORD
	v_and_b32_sdwa v6, v50, v22 dst_sel:DWORD dst_unused:UNUSED_PAD src0_sel:WORD_1 src1_sel:DWORD
	v_and_b32_sdwa v23, v48, v22 dst_sel:DWORD dst_unused:UNUSED_PAD src0_sel:WORD_1 src1_sel:DWORD
	v_add3_u32 v5, v51, v5, s18
	v_add3_u32 v7, v49, v7, s18
	v_add3_u32 v23, v48, v23, s18
	v_add3_u32 v6, v50, v6, s18
	v_and_b32_e32 v5, 0xffff0000, v5
	v_and_b32_e32 v7, 0xffff0000, v7
	s_add_u32 s24, s12, 0xc0000
	s_addc_u32 s25, s13, 0
	v_or_b32_sdwa v77, v5, v6 dst_sel:DWORD dst_unused:UNUSED_PAD src0_sel:DWORD src1_sel:WORD_1
	v_or_b32_sdwa v76, v7, v23 dst_sel:DWORD dst_unused:UNUSED_PAD src0_sel:DWORD src1_sel:WORD_1
	v_mul_f32_e32 v3, v49, v49
	v_mul_f32_e32 v4, v51, v51
	global_store_dwordx2 v11, v[76:77], s[24:25] nt
	v_fmac_f32_e32 v3, v48, v48
	v_fmac_f32_e32 v4, v50, v50
	v_add_f32_e32 v3, v3, v4
	v_add_f32_e32 v2, v2, v3
	s_mov_b64 exec, s[20:21]
	global_load_dwordx4 v[48:51], v10, s[14:15] offset:2048 nt
	s_mov_b64 exec, s[22:23]
	s_waitcnt vmcnt(8)
	v_and_b32_sdwa v5, v55, v22 dst_sel:DWORD dst_unused:UNUSED_PAD src0_sel:WORD_1 src1_sel:DWORD
	v_and_b32_sdwa v7, v53, v22 dst_sel:DWORD dst_unused:UNUSED_PAD src0_sel:WORD_1 src1_sel:DWORD
	v_and_b32_sdwa v6, v54, v22 dst_sel:DWORD dst_unused:UNUSED_PAD src0_sel:WORD_1 src1_sel:DWORD
	v_and_b32_sdwa v23, v52, v22 dst_sel:DWORD dst_unused:UNUSED_PAD src0_sel:WORD_1 src1_sel:DWORD
	v_add3_u32 v5, v55, v5, s18
	v_add3_u32 v7, v53, v7, s18
	v_add3_u32 v23, v52, v23, s18
	v_add3_u32 v6, v54, v6, s18
	v_and_b32_e32 v5, 0xffff0000, v5
	v_and_b32_e32 v7, 0xffff0000, v7
	s_add_u32 s24, s12, 0xe0000
	s_addc_u32 s25, s13, 0
	v_or_b32_sdwa v79, v5, v6 dst_sel:DWORD dst_unused:UNUSED_PAD src0_sel:DWORD src1_sel:WORD_1
	v_or_b32_sdwa v78, v7, v23 dst_sel:DWORD dst_unused:UNUSED_PAD src0_sel:DWORD src1_sel:WORD_1
	v_mul_f32_e32 v3, v53, v53
	v_mul_f32_e32 v4, v55, v55
	global_store_dwordx2 v11, v[78:79], s[24:25] nt
	v_fmac_f32_e32 v3, v52, v52
	v_fmac_f32_e32 v4, v54, v54
	v_add_f32_e32 v3, v3, v4
	v_add_f32_e32 v2, v2, v3
	s_mov_b64 exec, s[20:21]
	global_load_dwordx4 v[52:55], v10, s[14:15] offset:3072 nt
	s_mov_b64 exec, s[22:23]
	s_branch .Lxcv_tail
.Lxcv_first:
	s_waitcnt vmcnt(7)
	v_and_b32_sdwa v5, v27, v22 dst_sel:DWORD dst_unused:UNUSED_PAD src0_sel:WORD_1 src1_sel:DWORD
	v_and_b32_sdwa v7, v25, v22 dst_sel:DWORD dst_unused:UNUSED_PAD src0_sel:WORD_1 src1_sel:DWORD
	v_and_b32_sdwa v6, v26, v22 dst_sel:DWORD dst_unused:UNUSED_PAD src0_sel:WORD_1 src1_sel:DWORD
	v_and_b32_sdwa v23, v24, v22 dst_sel:DWORD dst_unused:UNUSED_PAD src0_sel:WORD_1 src1_sel:DWORD
	v_add3_u32 v5, v27, v5, s18
	v_add3_u32 v7, v25, v7, s18
	v_add3_u32 v23, v24, v23, s18
	v_add3_u32 v6, v26, v6, s18
	v_and_b32_e32 v5, 0xffff0000, v5
	v_and_b32_e32 v7, 0xffff0000, v7
	v_or_b32_sdwa v65, v5, v6 dst_sel:DWORD dst_unused:UNUSED_PAD src0_sel:DWORD src1_sel:WORD_1
	v_or_b32_sdwa v64, v7, v23 dst_sel:DWORD dst_unused:UNUSED_PAD src0_sel:DWORD src1_sel:WORD_1
	v_mul_f32_e32 v3, v25, v25
	v_mul_f32_e32 v4, v27, v27
	global_store_dwordx2 v11, v[64:65], s[12:13] nt
	v_fmac_f32_e32 v3, v24, v24
	v_fmac_f32_e32 v4, v26, v26
	v_add_f32_e32 v2, v3, v4
	s_mov_b64 exec, s[20:21]
	global_load_dwordx4 v[24:27], v10, s[14:15] offset:-4096 nt
	s_mov_b64 exec, s[22:23]
	s_waitcnt vmcnt(7)
	v_and_b32_sdwa v5, v31, v22 dst_sel:DWORD dst_unused:UNUSED_PAD src0_sel:WORD_1 src1_sel:DWORD
	v_and_b32_sdwa v7, v29, v22 dst_sel:DWORD dst_unused:UNUSED_PAD src0_sel:WORD_1 src1_sel:DWORD
	v_and_b32_sdwa v6, v30, v22 dst_sel:DWORD dst_unused:UNUSED_PAD src0_sel:WORD_1 src1_sel:DWORD
	v_and_b32_sdwa v23, v28, v22 dst_sel:DWORD dst_unused:UNUSED_PAD src0_sel:WORD_1 src1_sel:DWORD
	v_add3_u32 v5, v31, v5, s18
	v_add3_u32 v7, v29, v7, s18
	v_add3_u32 v23, v28, v23, s18
	v_add3_u32 v6, v30, v6, s18
	v_and_b32_e32 v5, 0xffff0000, v5
	v_and_b32_e32 v7, 0xffff0000, v7
	s_add_u32 s24, s12, 0x20000
	s_addc_u32 s25, s13, 0
	v_or_b32_sdwa v67, v5, v6 dst_sel:DWORD dst_unused:UNUSED_PAD src0_sel:DWORD src1_sel:WORD_1
	v_or_b32_sdwa v66, v7, v23 dst_sel:DWORD dst_unused:UNUSED_PAD src0_sel:DWORD src1_sel:WORD_1
	v_mul_f32_e32 v3, v29, v29
	v_mul_f32_e32 v4, v31, v31
	global_store_dwordx2 v11, v[66:67], s[24:25] nt
	v_fmac_f32_e32 v3, v28, v28
	v_fmac_f32_e32 v4, v30, v30
	v_add_f32_e32 v3, v3, v4
	v_add_f32_e32 v2, v2, v3
	s_mov_b64 exec, s[20:21]
	global_load_dwordx4 v[28:31], v10, s[14:15] offset:-3072 nt
	s_mov_b64 exec, s[22:23]
	s_waitcnt vmcnt(7)
; __device__ __forceinline__ unsigned pk2(float lo, float hi) { return f2bf(lo) | (f2bf(hi) << 16); }
; __device__ __forceinline__ void p0_prologue(const Args& a, LAS unsigned char* lds) {
;     ...
;     { const float* x = a.in[0]; bf16* xb = (bf16*)(ws + WS_XB0); float* ss0 = (float*)(ws + WS_SS0);
;       for (int m = gw; m < M; m += NGW) { const f32x4* xr = (const f32x4*)(x + (size_t)m * D) + lane; u32x2* o8 = (u32x2*)(xb + (size_t)(m >> 8) * 8 * 65536 + (size_t)(m & 255) * 256) + lane; float s = 0.f;
; #pragma unroll
;           for (int j = 0; j < 8; ++j) { const f32x4 v = __builtin_nontemporal_load(xr + 64 * j); s += (v[0] * v[0] + v[1] * v[1]) + (v[2] * v[2] + v[3] * v[3]); u32x2 w; w.x = pk2(v[0], v[1]); w.y = pk2(v[2], v[3]); o8[(size_t)j * (65536 / 4)] = w; }
;           s = wave_sum(s); if (lane < 32) ss0[(size_t)m * 32 + lane] = lane == 0 ? s : 0.f; } }
	v_and_b32_sdwa v5, v35, v22 dst_sel:DWORD dst_unused:UNUSED_PAD src0_sel:WORD_1 src1_sel:DWORD
	v_and_b32_sdwa v7, v33, v22 dst_sel:DWORD dst_unused:UNUSED_PAD src0_sel:WORD_1 src1_sel:DWORD
	v_and_b32_sdwa v6, v34, v22 dst_sel:DWORD dst_unused:UNUSED_PAD src0_sel:WORD_1 src1_sel:DWORD
	v_and_b32_sdwa v23, v32, v22 dst_sel:DWORD dst_unused:UNUSED_PAD src0_sel:WORD_1 src1_sel:DWORD
	v_add3_u32 v5, v35, v5, s18
	v_add3_u32 v7, v33, v7, s18
	v_add3_u32 v23, v32, v23, s18
	v_add3_u32 v6, v34, v6, s18
	v_and_b32_e32 v5, 0xffff0000, v5
	v_and_b32_e32 v7, 0xffff0000, v7
	s_add_u32 s24, s12, 0x40000
	s_addc_u32 s25, s13, 0
	v_or_b32_sdwa v69, v5, v6 dst_sel:DWORD dst_unused:UNUSED_PAD src0_sel:DWORD src1_sel:WORD_1
	v_or_b32_sdwa v68, v7, v23 dst_sel:DWORD dst_unused:UNUSED_PAD src0_sel:DWORD src1_sel:WORD_1
	v_mul_f32_e32 v3, v33, v33
	v_mul_f32_e32 v4, v35, v35
	global_store_dwordx2 v11, v[68:69], s[24:25] nt
	v_fmac_f32_e32 v3, v32, v32
	v_fmac_f32_e32 v4, v34, v34
	v_add_f32_e32 v3, v3, v4
	v_add_f32_e32 v2, v2, v3
	s_mov_b64 exec, s[20:21]
	global_load_dwordx4 v[32:35], v10, s[14:15] offset:-2048 nt
	s_mov_b64 exec, s[22:23]
	s_waitcnt vmcnt(7)
	v_and_b32_sdwa v5, v39, v22 dst_sel:DWORD dst_unused:UNUSED_PAD src0_sel:WORD_1 src1_sel:DWORD
	v_and_b32_sdwa v7, v37, v22 dst_sel:DWORD dst_unused:UNUSED_PAD src0_sel:WORD_1 src1_sel:DWORD
	v_and_b32_sdwa v6, v38, v22 dst_sel:DWORD dst_unused:UNUSED_PAD src0_sel:WORD_1 src1_sel:DWORD
	v_and_b32_sdwa v23, v36, v22 dst_sel:DWORD dst_unused:UNUSED_PAD src0_sel:WORD_1 src1_sel:DWORD
	v_add3_u32 v5, v39, v5, s18
	v_add3_u32 v7, v37, v7, s18
	v_add3_u32 v23, v36, v23, s18
	v_add3_u32 v6, v38, v6, s18
	v_and_b32_e32 v5, 0xffff0000, v5
	v_and_b32_e32 v7, 0xffff0000, v7
	s_add_u32 s24, s12, 0x60000
	s_addc_u32 s25, s13, 0
	v_or_b32_sdwa v71, v5, v6 dst_sel:DWORD dst_unused:UNUSED_PAD src0_sel:DWORD src1_sel:WORD_1
	v_or_b32_sdwa v70, v7, v23 dst_sel:DWORD dst_unused:UNUSED_PAD src0_sel:DWORD src1_sel:WORD_1
	v_mul_f32_e32 v3, v37, v37
	v_mul_f32_e32 v4, v39, v39
	global_store_dwordx2 v11, v[70:71], s[24:25] nt
	v_fmac_f32_e32 v3, v36, v36
	v_fmac_f32_e32 v4, v38, v38
	v_add_f32_e32 v3, v3, v4
	v_add_f32_e32 v2, v2, v3
	s_mov_b64 exec, s[20:21]
	global_load_dwordx4 v[36:39], v10, s[14:15] offset:-1024 nt
	s_mov_b64 exec, s[22:23]
	s_waitcnt vmcnt(7)
	v_and_b32_sdwa v5, v43, v22 dst_sel:DWORD dst_unused:UNUSED_PAD src0_sel:WORD_1 src1_sel:DWORD
	v_and_b32_sdwa v7, v41, v22 dst_sel:DWORD dst_unused:UNUSED_PAD src0_sel:WORD_1 src1_sel:DWORD
	v_and_b32_sdwa v6, v42, v22 dst_sel:DWORD dst_unused:UNUSED_PAD src0_sel:WORD_1 src1_sel:DWORD
	v_and_b32_sdwa v23, v40, v22 dst_sel:DWORD dst_unused:UNUSED_PAD src0_sel:WORD_1 src1_sel:DWORD
	v_add3_u32 v5, v43, v5, s18
	v_add3_u32 v7, v41, v7, s18
	v_add3_u32 v23, v40, v23, s18
	v_add3_u32 v6, v42, v6, s18
	v_and_b32_e32 v5, 0xffff0000, v5
	v_and_b32_e32 v7, 0xffff0000, v7
	s_add_u32 s24, s12, 0x80000
	s_addc_u32 s25, s13, 0
	v_or_b32_sdwa v73, v5, v6 dst_sel:DWORD dst_unused:UNUSED_PAD src0_sel:DWORD src1_sel:WORD_1
	v_or_b32_sdwa v72, v7, v23 dst_sel:DWORD dst_unused:UNUSED_PAD src0_sel:DWORD src1_sel:WORD_1
	v_mul_f32_e32 v3, v41, v41
	v_mul_f32_e32 v4, v43, v43
	global_store_dwordx2 v11, v[72:73], s[24:25] nt
	v_fmac_f32_e32 v3, v40, v40
	v_fmac_f32_e32 v4, v42, v42
	v_add_f32_e32 v3, v3, v4
	v_add_f32_e32 v2, v2, v3
	s_mov_b64 exec, s[20:21]
	global_load_dwordx4 v[40:43], v10, s[14:15] offset:0 nt
	s_mov_b64 exec, s[22:23]
	s_waitcnt vmcnt(7)
	v_and_b32_sdwa v5, v47, v22 dst_sel:DWORD dst_unused:UNUSED_PAD src0_sel:WORD_1 src1_sel:DWORD
	v_and_b32_sdwa v7, v45, v22 dst_sel:DWORD dst_unused:UNUSED_PAD src0_sel:WORD_1 src1_sel:DWORD
	v_and_b32_sdwa v6, v46, v22 dst_sel:DWORD dst_unused:UNUSED_PAD src0_sel:WORD_1 src1_sel:DWORD
	v_and_b32_sdwa v23, v44, v22 dst_sel:DWORD dst_unused:UNUSED_PAD src0_sel:WORD_1 src1_sel:DWORD
	v_add3_u32 v5, v47, v5, s18
	v_add3_u32 v7, v45, v7, s18
	v_add3_u32 v23, v44, v23, s18
	v_add3_u32 v6, v46, v6, s18
	v_and_b32_e32 v5, 0xffff0000, v5
	v_and_b32_e32 v7, 0xffff0000, v7
	s_add_u32 s24, s12, 0xa0000
	s_addc_u32 s25, s13, 0
	v_or_b32_sdwa v75, v5, v6 dst_sel:DWORD dst_unused:UNUSED_PAD src0_sel:DWORD src1_sel:WORD_1
	v_or_b32_sdwa v74, v7, v23 dst_sel:DWORD dst_unused:UNUSED_PAD src0_sel:DWORD src1_sel:WORD_1
	v_mul_f32_e32 v3, v45, v45
	v_mul_f32_e32 v4, v47, v47
	global_store_dwordx2 v11, v[74:75], s[24:25] nt
	v_fmac_f32_e32 v3, v44, v44
	v_fmac_f32_e32 v4, v46, v46
	v_add_f32_e32 v3, v3, v4
	v_add_f32_e32 v2, v2, v3
	s_mov_b64 exec, s[20:21]
	global_load_dwordx4 v[44:47], v10, s[14:15] offset:1024 nt
	s_mov_b64 exec, s[22:23]
	s_waitcnt vmcnt(7)
	v_and_b32_sdwa v5, v51, v22 dst_sel:DWORD dst_unused:UNUSED_PAD src0_sel:WORD_1 src1_sel:DWORD
	v_and_b32_sdwa v7, v49, v22 dst_sel:DWORD dst_unused:UNUSED_PAD src0_sel:WORD_1 src1_sel:DWORD
	v_and_b32_sdwa v6, v50, v22 dst_sel:DWORD dst_unused:UNUSED_PAD src0_sel:WORD_1 src1_sel:DWORD
	v_and_b32_sdwa v23, v48, v22 dst_sel:DWORD dst_unused:UNUSED_PAD src0_sel:WORD_1 src1_sel:DWORD
	v_add3_u32 v5, v51, v5, s18
	v_add3_u32 v7, v49, v7, s18
	v_add3_u32 v23, v48, v23, s18
	v_add3_u32 v6, v50, v6, s18
	v_and_b32_e32 v5, 0xffff0000, v5
	v_and_b32_e32 v7, 0xffff0000, v7
	s_add_u32 s24, s12, 0xc0000
	s_addc_u32 s25, s13, 0
	v_or_b32_sdwa v77, v5, v6 dst_sel:DWORD dst_unused:UNUSED_PAD src0_sel:DWORD src1_sel:WORD_1
	v_or_b32_sdwa v76, v7, v23 dst_sel:DWORD dst_unused:UNUSED_PAD src0_sel:DWORD src1_sel:WORD_1
	v_mul_f32_e32 v3, v49, v49
	v_mul_f32_e32 v4, v51, v51
	global_store_dwordx2 v11, v[76:77], s[24:25] nt
	v_fmac_f32_e32 v3, v48, v48
	v_fmac_f32_e32 v4, v50, v50
	v_add_f32_e32 v3, v3, v4
	v_add_f32_e32 v2, v2, v3
	s_mov_b64 exec, s[20:21]
	global_load_dwordx4 v[48:51], v10, s[14:15] offset:2048 nt
	s_mov_b64 exec, s[22:23]
	s_waitcnt vmcnt(7)
	v_and_b32_sdwa v5, v55, v22 dst_sel:DWORD dst_unused:UNUSED_PAD src0_sel:WORD_1 src1_sel:DWORD
	v_and_b32_sdwa v7, v53, v22 dst_sel:DWORD dst_unused:UNUSED_PAD src0_sel:WORD_1 src1_sel:DWORD
	v_and_b32_sdwa v6, v54, v22 dst_sel:DWORD dst_unused:UNUSED_PAD src0_sel:WORD_1 src1_sel:DWORD
	v_and_b32_sdwa v23, v52, v22 dst_sel:DWORD dst_unused:UNUSED_PAD src0_sel:WORD_1 src1_sel:DWORD
	v_add3_u32 v5, v55, v5, s18
	v_add3_u32 v7, v53, v7, s18
	v_add3_u32 v23, v52, v23, s18
	v_add3_u32 v6, v54, v6, s18
	v_and_b32_e32 v5, 0xffff0000, v5
	v_and_b32_e32 v7, 0xffff0000, v7
	s_add_u32 s24, s12, 0xe0000
	s_addc_u32 s25, s13, 0
	v_or_b32_sdwa v79, v5, v6 dst_sel:DWORD dst_unused:UNUSED_PAD src0_sel:DWORD src1_sel:WORD_1
	v_or_b32_sdwa v78, v7, v23 dst_sel:DWORD dst_unused:UNUSED_PAD src0_sel:DWORD src1_sel:WORD_1
	v_mul_f32_e32 v3, v53, v53
	v_mul_f32_e32 v4, v55, v55
	global_store_dwordx2 v11, v[78:79], s[24:25] nt
	v_fmac_f32_e32 v3, v52, v52
	v_fmac_f32_e32 v4, v54, v54
	v_add_f32_e32 v3, v3, v4
	v_add_f32_e32 v2, v2, v3
	s_mov_b64 exec, s[20:21]
	global_load_dwordx4 v[52:55], v10, s[14:15] offset:3072 nt
	s_mov_b64 exec, s[22:23]
	s_branch .Lxcv_tail
; __device__ __forceinline__ unsigned pk2(float lo, float hi) { return f2bf(lo) | (f2bf(hi) << 16); }
; __device__ __forceinline__ void p0_prologue(const Args& a, LAS unsigned char* lds) {
;     ...
;     { const float* x = a.in[0]; bf16* xb = (bf16*)(ws + WS_XB0); float* ss0 = (float*)(ws + WS_SS0);
;       for (int m = gw; m < M; m += NGW) { const f32x4* xr = (const f32x4*)(x + (size_t)m * D) + lane; u32x2* o8 = (u32x2*)(xb + (size_t)(m >> 8) * 8 * 65536 + (size_t)(m & 255) * 256) + lane; float s = 0.f;
; #pragma unroll
;           for (int j = 0; j < 8; ++j) { const f32x4 v = __builtin_nontemporal_load(xr + 64 * j); s += (v[0] * v[0] + v[1] * v[1]) + (v[2] * v[2] + v[3] * v[3]); u32x2 w; w.x = pk2(v[0], v[1]); w.y = pk2(v[2], v[3]); o8[(size_t)j * (65536 / 4)] = w; }
;           s = wave_sum(s); if (lane < 32) ss0[(size_t)m * 32 + lane] = lane == 0 ? s : 0.f; } }
.Lxcv_mid:
	s_waitcnt vmcnt(15)
	v_and_b32_sdwa v5, v27, v22 dst_sel:DWORD dst_unused:UNUSED_PAD src0_sel:WORD_1 src1_sel:DWORD
	v_and_b32_sdwa v7, v25, v22 dst_sel:DWORD dst_unused:UNUSED_PAD src0_sel:WORD_1 src1_sel:DWORD
	v_and_b32_sdwa v6, v26, v22 dst_sel:DWORD dst_unused:UNUSED_PAD src0_sel:WORD_1 src1_sel:DWORD
	v_and_b32_sdwa v23, v24, v22 dst_sel:DWORD dst_unused:UNUSED_PAD src0_sel:WORD_1 src1_sel:DWORD
	v_add3_u32 v5, v27, v5, s18
	v_add3_u32 v7, v25, v7, s18
	v_add3_u32 v23, v24, v23, s18
	v_add3_u32 v6, v26, v6, s18
	v_and_b32_e32 v5, 0xffff0000, v5
	v_and_b32_e32 v7, 0xffff0000, v7
	v_or_b32_sdwa v65, v5, v6 dst_sel:DWORD dst_unused:UNUSED_PAD src0_sel:DWORD src1_sel:WORD_1
	v_or_b32_sdwa v64, v7, v23 dst_sel:DWORD dst_unused:UNUSED_PAD src0_sel:DWORD src1_sel:WORD_1
	v_mul_f32_e32 v3, v25, v25
	v_mul_f32_e32 v4, v27, v27
	global_store_dwordx2 v11, v[64:65], s[12:13] nt
	v_fmac_f32_e32 v3, v24, v24
	v_fmac_f32_e32 v4, v26, v26
	v_add_f32_e32 v2, v3, v4
	s_mov_b64 exec, s[20:21]
	global_load_dwordx4 v[24:27], v10, s[14:15] offset:-4096 nt
	s_mov_b64 exec, s[22:23]
	s_waitcnt vmcnt(15)
	v_and_b32_sdwa v5, v31, v22 dst_sel:DWORD dst_unused:UNUSED_PAD src0_sel:WORD_1 src1_sel:DWORD
	v_and_b32_sdwa v7, v29, v22 dst_sel:DWORD dst_unused:UNUSED_PAD src0_sel:WORD_1 src1_sel:DWORD
	v_and_b32_sdwa v6, v30, v22 dst_sel:DWORD dst_unused:UNUSED_PAD src0_sel:WORD_1 src1_sel:DWORD
	v_and_b32_sdwa v23, v28, v22 dst_sel:DWORD dst_unused:UNUSED_PAD src0_sel:WORD_1 src1_sel:DWORD
	v_add3_u32 v5, v31, v5, s18
	v_add3_u32 v7, v29, v7, s18
	v_add3_u32 v23, v28, v23, s18
	v_add3_u32 v6, v30, v6, s18
	v_and_b32_e32 v5, 0xffff0000, v5
	v_and_b32_e32 v7, 0xffff0000, v7
	s_add_u32 s24, s12, 0x20000
	s_addc_u32 s25, s13, 0
	v_or_b32_sdwa v67, v5, v6 dst_sel:DWORD dst_unused:UNUSED_PAD src0_sel:DWORD src1_sel:WORD_1
	v_or_b32_sdwa v66, v7, v23 dst_sel:DWORD dst_unused:UNUSED_PAD src0_sel:DWORD src1_sel:WORD_1
	v_mul_f32_e32 v3, v29, v29
	v_mul_f32_e32 v4, v31, v31
	global_store_dwordx2 v11, v[66:67], s[24:25] nt
	v_fmac_f32_e32 v3, v28, v28
	v_fmac_f32_e32 v4, v30, v30
	v_add_f32_e32 v3, v3, v4
	v_add_f32_e32 v2, v2, v3
	s_mov_b64 exec, s[20:21]
	global_load_dwordx4 v[28:31], v10, s[14:15] offset:-3072 nt
	s_mov_b64 exec, s[22:23]
	s_waitcnt vmcnt(15)
	v_and_b32_sdwa v5, v35, v22 dst_sel:DWORD dst_unused:UNUSED_PAD src0_sel:WORD_1 src1_sel:DWORD
	v_and_b32_sdwa v7, v33, v22 dst_sel:DWORD dst_unused:UNUSED_PAD src0_sel:WORD_1 src1_sel:DWORD
	v_and_b32_sdwa v6, v34, v22 dst_sel:DWORD dst_unused:UNUSED_PAD src0_sel:WORD_1 src1_sel:DWORD
	v_and_b32_sdwa v23, v32, v22 dst_sel:DWORD dst_unused:UNUSED_PAD src0_sel:WORD_1 src1_sel:DWORD
	v_add3_u32 v5, v35, v5, s18
	v_add3_u32 v7, v33, v7, s18
	v_add3_u32 v23, v32, v23, s18
	v_add3_u32 v6, v34, v6, s18
	v_and_b32_e32 v5, 0xffff0000, v5
	v_and_b32_e32 v7, 0xffff0000, v7
	s_add_u32 s24, s12, 0x40000
	s_addc_u32 s25, s13, 0
	v_or_b32_sdwa v69, v5, v6 dst_sel:DWORD dst_unused:UNUSED_PAD src0_sel:DWORD src1_sel:WORD_1
	v_or_b32_sdwa v68, v7, v23 dst_sel:DWORD dst_unused:UNUSED_PAD src0_sel:DWORD src1_sel:WORD_1
	v_mul_f32_e32 v3, v33, v33
	v_mul_f32_e32 v4, v35, v35
	global_store_dwordx2 v11, v[68:69], s[24:25] nt
	v_fmac_f32_e32 v3, v32, v32
	v_fmac_f32_e32 v4, v34, v34
	v_add_f32_e32 v3, v3, v4
	v_add_f32_e32 v2, v2, v3
	s_mov_b64 exec, s[20:21]
	global_load_dwordx4 v[32:35], v10, s[14:15] offset:-2048 nt
	s_mov_b64 exec, s[22:23]
	s_waitcnt vmcnt(15)
	v_and_b32_sdwa v5, v39, v22 dst_sel:DWORD dst_unused:UNUSED_PAD src0_sel:WORD_1 src1_sel:DWORD
	v_and_b32_sdwa v7, v37, v22 dst_sel:DWORD dst_unused:UNUSED_PAD src0_sel:WORD_1 src1_sel:DWORD
	v_and_b32_sdwa v6, v38, v22 dst_sel:DWORD dst_unused:UNUSED_PAD src0_sel:WORD_1 src1_sel:DWORD
	v_and_b32_sdwa v23, v36, v22 dst_sel:DWORD dst_unused:UNUSED_PAD src0_sel:WORD_1 src1_sel:DWORD
	v_add3_u32 v5, v39, v5, s18
	v_add3_u32 v7, v37, v7, s18
	v_add3_u32 v23, v36, v23, s18
	v_add3_u32 v6, v38, v6, s18
	v_and_b32_e32 v5, 0xffff0000, v5
	v_and_b32_e32 v7, 0xffff0000, v7
	s_add_u32 s24, s12, 0x60000
	s_addc_u32 s25, s13, 0
	v_or_b32_sdwa v71, v5, v6 dst_sel:DWORD dst_unused:UNUSED_PAD src0_sel:DWORD src1_sel:WORD_1
	v_or_b32_sdwa v70, v7, v23 dst_sel:DWORD dst_unused:UNUSED_PAD src0_sel:DWORD src1_sel:WORD_1
	v_mul_f32_e32 v3, v37, v37
	v_mul_f32_e32 v4, v39, v39
	global_store_dwordx2 v11, v[70:71], s[24:25] nt
	v_fmac_f32_e32 v3, v36, v36
	v_fmac_f32_e32 v4, v38, v38
	v_add_f32_e32 v3, v3, v4
	v_add_f32_e32 v2, v2, v3
	s_mov_b64 exec, s[20:21]
	global_load_dwordx4 v[36:39], v10, s[14:15] offset:-1024 nt
	s_mov_b64 exec, s[22:23]
	s_waitcnt vmcnt(15)
; __device__ __forceinline__ unsigned pk2(float lo, float hi) { return f2bf(lo) | (f2bf(hi) << 16); }
; __device__ __forceinline__ void p0_prologue(const Args& a, LAS unsigned char* lds) {
;     ...
;     { const float* x = a.in[0]; bf16* xb = (bf16*)(ws + WS_XB0); float* ss0 = (float*)(ws + WS_SS0);
;       for (int m = gw; m < M; m += NGW) { const f32x4* xr = (const f32x4*)(x + (size_t)m * D) + lane; u32x2* o8 = (u32x2*)(xb + (size_t)(m >> 8) * 8 * 65536 + (size_t)(m & 255) * 256) + lane; float s = 0.f;
; #pragma unroll
;           for (int j = 0; j < 8; ++j) { const f32x4 v = __builtin_nontemporal_load(xr + 64 * j); s += (v[0] * v[0] + v[1] * v[1]) + (v[2] * v[2] + v[3] * v[3]); u32x2 w; w.x = pk2(v[0], v[1]); w.y = pk2(v[2], v[3]); o8[(size_t)j * (65536 / 4)] = w; }
;           s = wave_sum(s); if (lane < 32) ss0[(size_t)m * 32 + lane] = lane == 0 ? s : 0.f; } }
	v_and_b32_sdwa v5, v43, v22 dst_sel:DWORD dst_unused:UNUSED_PAD src0_sel:WORD_1 src1_sel:DWORD
	v_and_b32_sdwa v7, v41, v22 dst_sel:DWORD dst_unused:UNUSED_PAD src0_sel:WORD_1 src1_sel:DWORD
	v_and_b32_sdwa v6, v42, v22 dst_sel:DWORD dst_unused:UNUSED_PAD src0_sel:WORD_1 src1_sel:DWORD
	v_and_b32_sdwa v23, v40, v22 dst_sel:DWORD dst_unused:UNUSED_PAD src0_sel:WORD_1 src1_sel:DWORD
	v_add3_u32 v5, v43, v5, s18
	v_add3_u32 v7, v41, v7, s18
	v_add3_u32 v23, v40, v23, s18
	v_add3_u32 v6, v42, v6, s18
	v_and_b32_e32 v5, 0xffff0000, v5
	v_and_b32_e32 v7, 0xffff0000, v7
	s_add_u32 s24, s12, 0x80000
	s_addc_u32 s25, s13, 0
	v_or_b32_sdwa v73, v5, v6 dst_sel:DWORD dst_unused:UNUSED_PAD src0_sel:DWORD src1_sel:WORD_1
	v_or_b32_sdwa v72, v7, v23 dst_sel:DWORD dst_unused:UNUSED_PAD src0_sel:DWORD src1_sel:WORD_1
	v_mul_f32_e32 v3, v41, v41
	v_mul_f32_e32 v4, v43, v43
	global_store_dwordx2 v11, v[72:73], s[24:25] nt
	v_fmac_f32_e32 v3, v40, v40
	v_fmac_f32_e32 v4, v42, v42
	v_add_f32_e32 v3, v3, v4
	v_add_f32_e32 v2, v2, v3
	s_mov_b64 exec, s[20:21]
	global_load_dwordx4 v[40:43], v10, s[14:15] offset:0 nt
	s_mov_b64 exec, s[22:23]
	s_waitcnt vmcnt(15)
	v_and_b32_sdwa v5, v47, v22 dst_sel:DWORD dst_unused:UNUSED_PAD src0_sel:WORD_1 src1_sel:DWORD
	v_and_b32_sdwa v7, v45, v22 dst_sel:DWORD dst_unused:UNUSED_PAD src0_sel:WORD_1 src1_sel:DWORD
	v_and_b32_sdwa v6, v46, v22 dst_sel:DWORD dst_unused:UNUSED_PAD src0_sel:WORD_1 src1_sel:DWORD
	v_and_b32_sdwa v23, v44, v22 dst_sel:DWORD dst_unused:UNUSED_PAD src0_sel:WORD_1 src1_sel:DWORD
	v_add3_u32 v5, v47, v5, s18
	v_add3_u32 v7, v45, v7, s18
	v_add3_u32 v23, v44, v23, s18
	v_add3_u32 v6, v46, v6, s18
	v_and_b32_e32 v5, 0xffff0000, v5
	v_and_b32_e32 v7, 0xffff0000, v7
	s_add_u32 s24, s12, 0xa0000
	s_addc_u32 s25, s13, 0
	v_or_b32_sdwa v75, v5, v6 dst_sel:DWORD dst_unused:UNUSED_PAD src0_sel:DWORD src1_sel:WORD_1
	v_or_b32_sdwa v74, v7, v23 dst_sel:DWORD dst_unused:UNUSED_PAD src0_sel:DWORD src1_sel:WORD_1
	v_mul_f32_e32 v3, v45, v45
	v_mul_f32_e32 v4, v47, v47
	global_store_dwordx2 v11, v[74:75], s[24:25] nt
	v_fmac_f32_e32 v3, v44, v44
	v_fmac_f32_e32 v4, v46, v46
	v_add_f32_e32 v3, v3, v4
	v_add_f32_e32 v2, v2, v3
	s_mov_b64 exec, s[20:21]
	global_load_dwordx4 v[44:47], v10, s[14:15] offset:1024 nt
	s_mov_b64 exec, s[22:23]
	s_waitcnt vmcnt(15)
	v_and_b32_sdwa v5, v51, v22 dst_sel:DWORD dst_unused:UNUSED_PAD src0_sel:WORD_1 src1_sel:DWORD
	v_and_b32_sdwa v7, v49, v22 dst_sel:DWORD dst_unused:UNUSED_PAD src0_sel:WORD_1 src1_sel:DWORD
	v_and_b32_sdwa v6, v50, v22 dst_sel:DWORD dst_unused:UNUSED_PAD src0_sel:WORD_1 src1_sel:DWORD
	v_and_b32_sdwa v23, v48, v22 dst_sel:DWORD dst_unused:UNUSED_PAD src0_sel:WORD_1 src1_sel:DWORD
	v_add3_u32 v5, v51, v5, s18
	v_add3_u32 v7, v49, v7, s18
	v_add3_u32 v23, v48, v23, s18
	v_add3_u32 v6, v50, v6, s18
	v_and_b32_e32 v5, 0xffff0000, v5
	v_and_b32_e32 v7, 0xffff0000, v7
	s_add_u32 s24, s12, 0xc0000
	s_addc_u32 s25, s13, 0
	v_or_b32_sdwa v77, v5, v6 dst_sel:DWORD dst_unused:UNUSED_PAD src0_sel:DWORD src1_sel:WORD_1
	v_or_b32_sdwa v76, v7, v23 dst_sel:DWORD dst_unused:UNUSED_PAD src0_sel:DWORD src1_sel:WORD_1
	v_mul_f32_e32 v3, v49, v49
	v_mul_f32_e32 v4, v51, v51
	global_store_dwordx2 v11, v[76:77], s[24:25] nt
	v_fmac_f32_e32 v3, v48, v48
	v_fmac_f32_e32 v4, v50, v50
	v_add_f32_e32 v3, v3, v4
	v_add_f32_e32 v2, v2, v3
	s_mov_b64 exec, s[20:21]
	global_load_dwordx4 v[48:51], v10, s[14:15] offset:2048 nt
	s_mov_b64 exec, s[22:23]
	s_waitcnt vmcnt(15)
	v_and_b32_sdwa v5, v55, v22 dst_sel:DWORD dst_unused:UNUSED_PAD src0_sel:WORD_1 src1_sel:DWORD
	v_and_b32_sdwa v7, v53, v22 dst_sel:DWORD dst_unused:UNUSED_PAD src0_sel:WORD_1 src1_sel:DWORD
	v_and_b32_sdwa v6, v54, v22 dst_sel:DWORD dst_unused:UNUSED_PAD src0_sel:WORD_1 src1_sel:DWORD
	v_and_b32_sdwa v23, v52, v22 dst_sel:DWORD dst_unused:UNUSED_PAD src0_sel:WORD_1 src1_sel:DWORD
	v_add3_u32 v5, v55, v5, s18
	v_add3_u32 v7, v53, v7, s18
	v_add3_u32 v23, v52, v23, s18
	v_add3_u32 v6, v54, v6, s18
	v_and_b32_e32 v5, 0xffff0000, v5
	v_and_b32_e32 v7, 0xffff0000, v7
	s_add_u32 s24, s12, 0xe0000
	s_addc_u32 s25, s13, 0
	v_or_b32_sdwa v79, v5, v6 dst_sel:DWORD dst_unused:UNUSED_PAD src0_sel:DWORD src1_sel:WORD_1
	v_or_b32_sdwa v78, v7, v23 dst_sel:DWORD dst_unused:UNUSED_PAD src0_sel:DWORD src1_sel:WORD_1
	v_mul_f32_e32 v3, v53, v53
	v_mul_f32_e32 v4, v55, v55
	global_store_dwordx2 v11, v[78:79], s[24:25] nt
	v_fmac_f32_e32 v3, v52, v52
	v_fmac_f32_e32 v4, v54, v54
	v_add_f32_e32 v3, v3, v4
	v_add_f32_e32 v2, v2, v3
	s_mov_b64 exec, s[20:21]
	global_load_dwordx4 v[52:55], v10, s[14:15] offset:3072 nt
	s_mov_b64 exec, s[22:23]

; __device__ __forceinline__ unsigned pk2(float lo, float hi) { return f2bf(lo) | (f2bf(hi) << 16); }
; __device__ __forceinline__ void p0_prologue(const Args& a, LAS unsigned char* lds) {
;     ...
;     { const float* p = a.in[1]; bf16* pb = (bf16*)(ws + WS_PB); const size_t n8 = (size_t)2 * M * PLE / 8;
;       for (size_t i = (size_t)blockIdx.x * 512 + tid; i < n8; i += (size_t)G * 512) { const f32x4 v0 = *(const f32x4*)(p + i * 8), v1 = *(const f32x4*)(p + i * 8 + 4);
;           u32x4 w; w.x = pk2(v0[0], v0[1]); w.y = pk2(v0[2], v0[3]); w.z = pk2(v1[0], v1[1]); w.w = pk2(v1[2], v1[3]); *(u32x4*)(pb + i * 8) = w; } }
.LBB0_326:
	global_load_dwordx4 v[8:11], v[4:5], off offset:-16
	global_load_dwordx4 v[12:15], v[4:5], off
	v_lshl_add_u64 v[2:3], v[2:3], 0, s[4:5]
	v_cmp_lt_u64_e32 vcc, s[12:13], v[2:3]
	v_lshl_add_u64 v[4:5], v[4:5], 0, s[6:7]
	s_or_b64 s[10:11], vcc, s[10:11]
	s_waitcnt vmcnt(1)
	v_bfe_u32 v1, v8, 16, 1
	v_bfe_u32 v16, v9, 16, 1
	v_bfe_u32 v17, v10, 16, 1
	v_bfe_u32 v18, v11, 16, 1
	s_waitcnt vmcnt(0)
	v_bfe_u32 v19, v12, 16, 1
	v_bfe_u32 v20, v13, 16, 1
	v_bfe_u32 v21, v14, 16, 1
	v_bfe_u32 v22, v15, 16, 1
	v_add3_u32 v1, v8, v1, s3
	v_add3_u32 v8, v9, v16, s3
	v_add3_u32 v9, v10, v17, s3
	v_add3_u32 v10, v11, v18, s3
	v_add3_u32 v11, v12, v19, s3
	v_add3_u32 v12, v13, v20, s3
	v_add3_u32 v13, v14, v21, s3
	v_add3_u32 v14, v15, v22, s3
	v_lshrrev_b32_e32 v1, 16, v1
	v_lshrrev_b32_e32 v9, 16, v9
	v_lshrrev_b32_e32 v11, 16, v11
	v_lshrrev_b32_e32 v13, 16, v13
	v_and_or_b32 v8, v8, s14, v1
	v_and_or_b32 v9, v10, s14, v9
	v_and_or_b32 v10, v12, s14, v11
	v_and_or_b32 v11, v14, s14, v13
	global_store_dwordx4 v[6:7], v[8:11], off nt
	v_lshl_add_u64 v[6:7], v[6:7], 0, s[8:9]
	s_andn2_b64 exec, exec, s[10:11]
	s_cbranch_execnz .LBB0_326
